# idxdma plus removal of redundant canonicalize v_max x,x in indexer scoring (exact no-op on MFMA results)
# speedup vs baseline: 1.0219x; 1.0029x over previous
.LBB0_404:
	s_or_b64 exec, exec, s[74:75]
	v_mfma_f32_32x32x16_bf16 v[18:33], v[38:41], v[58:61], 0
	v_mfma_f32_32x32x16_bf16 v[18:33], v[46:49], v[54:57], v[18:33]
	v_mfma_f32_32x32x16_bf16 v[18:33], v[34:37], v[50:53], v[18:33]
	v_mfma_f32_32x32x16_bf16 v[18:33], v[42:45], v[62:65], v[18:33]
	s_waitcnt vmcnt(12)
	ds_read_b128 v[58:61], v74 offset:8192
	ds_read_b128 v[54:57], v75 offset:8192
	ds_read_b128 v[50:53], v76 offset:8192
	ds_read_b128 v[62:65], v77 offset:8192
	s_nop 8
	v_max_f32_e32 v18, 0, v18
	v_max_f32_e32 v19, 0, v19
	v_fma_f32 v18, v174, v18, 0
	v_max_f32_e32 v20, 0, v20
	v_fmac_f32_e32 v18, v173, v19
	v_max_f32_e32 v21, 0, v21
	v_fmac_f32_e32 v18, v172, v20
	v_max_f32_e32 v22, 0, v22
	v_fmac_f32_e32 v18, v171, v21
	v_max_f32_e32 v23, 0, v23
	v_fmac_f32_e32 v18, v170, v22
	v_max_f32_e32 v24, 0, v24
	v_fmac_f32_e32 v18, v169, v23
	v_max_f32_e32 v25, 0, v25
	v_fmac_f32_e32 v18, v168, v24
	v_max_f32_e32 v26, 0, v26
	v_fmac_f32_e32 v18, v167, v25
	v_max_f32_e32 v27, 0, v27
	v_fmac_f32_e32 v18, v166, v26
	v_max_f32_e32 v28, 0, v28
	v_fmac_f32_e32 v18, v165, v27
	v_max_f32_e32 v29, 0, v29
	v_fmac_f32_e32 v18, v164, v28
	v_max_f32_e32 v30, 0, v30
	v_fmac_f32_e32 v18, v163, v29
	v_fmac_f32_e32 v18, v162, v30
	v_max_f32_e32 v19, 0, v31
	v_fmac_f32_e32 v18, v161, v19
	v_max_f32_e32 v19, 0, v32
	v_fmac_f32_e32 v18, v160, v19
	v_max_f32_e32 v19, 0, v33
	v_fmac_f32_e32 v18, v89, v19
	v_not_b32_e32 v19, v18
	v_or_b32_e32 v20, 0x80000000, v18
	v_cmp_gt_i32_e32 vcc, 0, v18
	s_nop 1
	v_cndmask_b32_e32 v18, v20, v19, vcc
	v_cmp_le_u32_e32 vcc, v96, v87
	s_nop 1
	v_cndmask_b32_e32 v175, 0, v18, vcc

.LBB0_408:
	s_or_b64 exec, exec, s[82:83]
	v_mfma_f32_32x32x16_bf16 v[18:33], v[38:41], v[58:61], 0
	v_mfma_f32_32x32x16_bf16 v[18:33], v[46:49], v[54:57], v[18:33]
	v_mfma_f32_32x32x16_bf16 v[18:33], v[34:37], v[50:53], v[18:33]
	v_mfma_f32_32x32x16_bf16 v[18:33], v[42:45], v[62:65], v[18:33]
	s_waitcnt vmcnt(12)
	ds_read_b128 v[58:61], v74 offset:12288
	ds_read_b128 v[54:57], v75 offset:12288
	ds_read_b128 v[50:53], v76 offset:12288
	ds_read_b128 v[62:65], v77 offset:12288
	s_nop 8
	v_max_f32_e32 v18, 0, v18
	v_max_f32_e32 v19, 0, v19
	v_fma_f32 v18, v174, v18, 0
	v_max_f32_e32 v20, 0, v20
	v_fmac_f32_e32 v18, v173, v19
	v_max_f32_e32 v21, 0, v21
	v_fmac_f32_e32 v18, v172, v20
	v_max_f32_e32 v22, 0, v22
	v_fmac_f32_e32 v18, v171, v21
	v_max_f32_e32 v23, 0, v23
	v_fmac_f32_e32 v18, v170, v22
	v_max_f32_e32 v24, 0, v24
	v_fmac_f32_e32 v18, v169, v23
	v_max_f32_e32 v25, 0, v25
	v_fmac_f32_e32 v18, v168, v24
	v_max_f32_e32 v26, 0, v26
	v_fmac_f32_e32 v18, v167, v25
	v_max_f32_e32 v27, 0, v27
	v_fmac_f32_e32 v18, v166, v26
	v_max_f32_e32 v28, 0, v28
	v_fmac_f32_e32 v18, v165, v27
	v_max_f32_e32 v29, 0, v29
	v_fmac_f32_e32 v18, v164, v28
	v_max_f32_e32 v30, 0, v30
	v_fmac_f32_e32 v18, v163, v29
	v_fmac_f32_e32 v18, v162, v30
	v_max_f32_e32 v19, 0, v31
	v_fmac_f32_e32 v18, v161, v19
	v_max_f32_e32 v19, 0, v32
	v_fmac_f32_e32 v18, v160, v19
	v_max_f32_e32 v19, 0, v33
	v_fmac_f32_e32 v18, v89, v19
	v_not_b32_e32 v19, v18
	v_or_b32_e32 v20, 0x80000000, v18
	v_cmp_gt_i32_e32 vcc, 0, v18
	s_nop 1
	v_cndmask_b32_e32 v18, v20, v19, vcc
	v_cmp_le_u32_e32 vcc, v97, v87
	s_nop 1
	v_cndmask_b32_e32 v176, 0, v18, vcc

.LBB0_412:
	s_or_b64 exec, exec, s[82:83]
	v_mfma_f32_32x32x16_bf16 v[18:33], v[38:41], v[58:61], 0
	v_mfma_f32_32x32x16_bf16 v[18:33], v[46:49], v[54:57], v[18:33]
	v_mfma_f32_32x32x16_bf16 v[18:33], v[34:37], v[50:53], v[18:33]
	v_mfma_f32_32x32x16_bf16 v[18:33], v[42:45], v[62:65], v[18:33]
	s_waitcnt vmcnt(12)
	ds_read_b128 v[58:61], v74 offset:0
	ds_read_b128 v[54:57], v75 offset:0
	ds_read_b128 v[50:53], v76 offset:0
	ds_read_b128 v[62:65], v77 offset:0
	s_nop 8
	v_max_f32_e32 v18, 0, v18
	v_max_f32_e32 v19, 0, v19
	v_fma_f32 v18, v174, v18, 0
	v_max_f32_e32 v20, 0, v20
	v_fmac_f32_e32 v18, v173, v19
	v_max_f32_e32 v21, 0, v21
	v_fmac_f32_e32 v18, v172, v20
	v_max_f32_e32 v22, 0, v22
	v_fmac_f32_e32 v18, v171, v21
	v_max_f32_e32 v23, 0, v23
	v_fmac_f32_e32 v18, v170, v22
	v_max_f32_e32 v24, 0, v24
	v_fmac_f32_e32 v18, v169, v23
	v_max_f32_e32 v25, 0, v25
	v_fmac_f32_e32 v18, v168, v24
	v_max_f32_e32 v26, 0, v26
	v_fmac_f32_e32 v18, v167, v25
	v_max_f32_e32 v27, 0, v27
	v_fmac_f32_e32 v18, v166, v26
	v_max_f32_e32 v28, 0, v28
	v_fmac_f32_e32 v18, v165, v27
	v_max_f32_e32 v29, 0, v29
	v_fmac_f32_e32 v18, v164, v28
	v_max_f32_e32 v30, 0, v30
	v_fmac_f32_e32 v18, v163, v29
	v_fmac_f32_e32 v18, v162, v30
	v_max_f32_e32 v19, 0, v31
	v_fmac_f32_e32 v18, v161, v19
	v_max_f32_e32 v19, 0, v32
	v_fmac_f32_e32 v18, v160, v19
	v_max_f32_e32 v19, 0, v33
	v_fmac_f32_e32 v18, v89, v19
	v_not_b32_e32 v19, v18
	v_or_b32_e32 v20, 0x80000000, v18
	v_cmp_gt_i32_e32 vcc, 0, v18
	s_nop 1
	v_cndmask_b32_e32 v18, v20, v19, vcc
	v_cmp_le_u32_e32 vcc, v98, v87
	s_nop 1
	v_cndmask_b32_e32 v179, 0, v18, vcc

.LBB0_416:
	s_or_b64 exec, exec, s[82:83]
	v_mfma_f32_32x32x16_bf16 v[18:33], v[38:41], v[58:61], 0
	v_mfma_f32_32x32x16_bf16 v[18:33], v[46:49], v[54:57], v[18:33]
	v_mfma_f32_32x32x16_bf16 v[18:33], v[34:37], v[50:53], v[18:33]
	v_mfma_f32_32x32x16_bf16 v[18:33], v[42:45], v[62:65], v[18:33]
	s_waitcnt vmcnt(12)
	ds_read_b128 v[58:61], v74 offset:4096
	ds_read_b128 v[54:57], v75 offset:4096
	ds_read_b128 v[50:53], v76 offset:4096
	ds_read_b128 v[62:65], v77 offset:4096
	s_nop 8
	v_max_f32_e32 v18, 0, v18
	v_max_f32_e32 v19, 0, v19
	v_fma_f32 v18, v174, v18, 0
	v_max_f32_e32 v20, 0, v20
	v_fmac_f32_e32 v18, v173, v19
	v_max_f32_e32 v21, 0, v21
	v_fmac_f32_e32 v18, v172, v20
	v_max_f32_e32 v22, 0, v22
	v_fmac_f32_e32 v18, v171, v21
	v_max_f32_e32 v23, 0, v23
	v_fmac_f32_e32 v18, v170, v22
	v_max_f32_e32 v24, 0, v24
	v_fmac_f32_e32 v18, v169, v23
	v_max_f32_e32 v25, 0, v25
	v_fmac_f32_e32 v18, v168, v24
	v_max_f32_e32 v26, 0, v26
	v_fmac_f32_e32 v18, v167, v25
	v_max_f32_e32 v27, 0, v27
	v_fmac_f32_e32 v18, v166, v26
	v_max_f32_e32 v28, 0, v28
	v_fmac_f32_e32 v18, v165, v27
	v_max_f32_e32 v29, 0, v29
	v_fmac_f32_e32 v18, v164, v28
	v_max_f32_e32 v30, 0, v30
	v_fmac_f32_e32 v18, v163, v29
	v_fmac_f32_e32 v18, v162, v30
	v_max_f32_e32 v19, 0, v31
	v_fmac_f32_e32 v18, v161, v19
	v_max_f32_e32 v19, 0, v32
	v_fmac_f32_e32 v18, v160, v19
	v_max_f32_e32 v19, 0, v33
	v_fmac_f32_e32 v18, v89, v19
	v_not_b32_e32 v19, v18
	v_or_b32_e32 v20, 0x80000000, v18
	v_cmp_gt_i32_e32 vcc, 0, v18
	s_nop 1
	v_cndmask_b32_e32 v18, v20, v19, vcc
	v_cmp_le_u32_e32 vcc, v99, v87
	s_nop 1
	v_cndmask_b32_e32 v180, 0, v18, vcc

.LBB0_420:
	s_or_b64 exec, exec, s[82:83]
	v_mfma_f32_32x32x16_bf16 v[18:33], v[38:41], v[58:61], 0
	v_mfma_f32_32x32x16_bf16 v[18:33], v[46:49], v[54:57], v[18:33]
	v_mfma_f32_32x32x16_bf16 v[18:33], v[34:37], v[50:53], v[18:33]
	v_mfma_f32_32x32x16_bf16 v[18:33], v[42:45], v[62:65], v[18:33]
	s_waitcnt vmcnt(12)
	ds_read_b128 v[58:61], v74 offset:8192
	ds_read_b128 v[54:57], v75 offset:8192
	ds_read_b128 v[50:53], v76 offset:8192
	ds_read_b128 v[62:65], v77 offset:8192
	s_nop 8
	v_max_f32_e32 v18, 0, v18
	v_max_f32_e32 v19, 0, v19
	v_fma_f32 v18, v174, v18, 0
	v_max_f32_e32 v20, 0, v20
	v_fmac_f32_e32 v18, v173, v19
	v_max_f32_e32 v21, 0, v21
	v_fmac_f32_e32 v18, v172, v20
	v_max_f32_e32 v22, 0, v22
	v_fmac_f32_e32 v18, v171, v21
	v_max_f32_e32 v23, 0, v23
	v_fmac_f32_e32 v18, v170, v22
	v_max_f32_e32 v24, 0, v24
	v_fmac_f32_e32 v18, v169, v23
	v_max_f32_e32 v25, 0, v25
	v_fmac_f32_e32 v18, v168, v24
	v_max_f32_e32 v26, 0, v26
	v_fmac_f32_e32 v18, v167, v25
	v_max_f32_e32 v27, 0, v27
	v_fmac_f32_e32 v18, v166, v26
	v_max_f32_e32 v28, 0, v28
	v_fmac_f32_e32 v18, v165, v27
	v_max_f32_e32 v29, 0, v29
	v_fmac_f32_e32 v18, v164, v28
	v_max_f32_e32 v30, 0, v30
	v_fmac_f32_e32 v18, v163, v29
	v_fmac_f32_e32 v18, v162, v30
	v_max_f32_e32 v19, 0, v31
	v_fmac_f32_e32 v18, v161, v19
	v_max_f32_e32 v19, 0, v32
	v_fmac_f32_e32 v18, v160, v19
	v_max_f32_e32 v19, 0, v33
	v_fmac_f32_e32 v18, v89, v19
	v_not_b32_e32 v19, v18
	v_or_b32_e32 v20, 0x80000000, v18
	v_cmp_gt_i32_e32 vcc, 0, v18
	s_nop 1
	v_cndmask_b32_e32 v18, v20, v19, vcc
	v_cmp_le_u32_e32 vcc, v100, v87
	s_nop 1
	v_cndmask_b32_e32 v181, 0, v18, vcc

.LBB0_424:
	s_or_b64 exec, exec, s[82:83]
	v_mfma_f32_32x32x16_bf16 v[18:33], v[38:41], v[58:61], 0
	v_mfma_f32_32x32x16_bf16 v[18:33], v[46:49], v[54:57], v[18:33]
	v_mfma_f32_32x32x16_bf16 v[18:33], v[34:37], v[50:53], v[18:33]
	v_mfma_f32_32x32x16_bf16 v[18:33], v[42:45], v[62:65], v[18:33]
	s_waitcnt vmcnt(12)
	ds_read_b128 v[58:61], v74 offset:12288
	ds_read_b128 v[54:57], v75 offset:12288
	ds_read_b128 v[50:53], v76 offset:12288
	ds_read_b128 v[62:65], v77 offset:12288
	s_nop 8
	v_max_f32_e32 v18, 0, v18
	v_max_f32_e32 v19, 0, v19
	v_fma_f32 v18, v174, v18, 0
	v_max_f32_e32 v20, 0, v20
	v_fmac_f32_e32 v18, v173, v19
	v_max_f32_e32 v21, 0, v21
	v_fmac_f32_e32 v18, v172, v20
	v_max_f32_e32 v22, 0, v22
	v_fmac_f32_e32 v18, v171, v21
	v_max_f32_e32 v23, 0, v23
	v_fmac_f32_e32 v18, v170, v22
	v_max_f32_e32 v24, 0, v24
	v_fmac_f32_e32 v18, v169, v23
	v_max_f32_e32 v25, 0, v25
	v_fmac_f32_e32 v18, v168, v24
	v_max_f32_e32 v26, 0, v26
	v_fmac_f32_e32 v18, v167, v25
	v_max_f32_e32 v27, 0, v27
	v_fmac_f32_e32 v18, v166, v26
	v_max_f32_e32 v28, 0, v28
	v_fmac_f32_e32 v18, v165, v27
	v_max_f32_e32 v29, 0, v29
	v_fmac_f32_e32 v18, v164, v28
	v_max_f32_e32 v30, 0, v30
	v_fmac_f32_e32 v18, v163, v29
	v_fmac_f32_e32 v18, v162, v30
	v_max_f32_e32 v19, 0, v31
	v_fmac_f32_e32 v18, v161, v19
	v_max_f32_e32 v19, 0, v32
	v_fmac_f32_e32 v18, v160, v19
	v_max_f32_e32 v19, 0, v33
	v_fmac_f32_e32 v18, v89, v19
	v_not_b32_e32 v19, v18
	v_or_b32_e32 v20, 0x80000000, v18
	v_cmp_gt_i32_e32 vcc, 0, v18
	s_nop 1
	v_cndmask_b32_e32 v18, v20, v19, vcc
	v_cmp_le_u32_e32 vcc, v101, v87
	s_nop 1
	v_cndmask_b32_e32 v182, 0, v18, vcc

.LBB0_428:
	s_or_b64 exec, exec, s[82:83]
	v_mfma_f32_32x32x16_bf16 v[18:33], v[38:41], v[58:61], 0
	v_mfma_f32_32x32x16_bf16 v[18:33], v[46:49], v[54:57], v[18:33]
	v_mfma_f32_32x32x16_bf16 v[18:33], v[34:37], v[50:53], v[18:33]
	v_mfma_f32_32x32x16_bf16 v[18:33], v[42:45], v[62:65], v[18:33]
	s_waitcnt vmcnt(12)
	ds_read_b128 v[58:61], v74 offset:0
	ds_read_b128 v[54:57], v75 offset:0
	ds_read_b128 v[50:53], v76 offset:0
	ds_read_b128 v[62:65], v77 offset:0
	s_nop 8
	v_max_f32_e32 v18, 0, v18
	v_max_f32_e32 v19, 0, v19
	v_fma_f32 v18, v174, v18, 0
	v_max_f32_e32 v20, 0, v20
	v_fmac_f32_e32 v18, v173, v19
	v_max_f32_e32 v21, 0, v21
	v_fmac_f32_e32 v18, v172, v20
	v_max_f32_e32 v22, 0, v22
	v_fmac_f32_e32 v18, v171, v21
	v_max_f32_e32 v23, 0, v23
	v_fmac_f32_e32 v18, v170, v22
	v_max_f32_e32 v24, 0, v24
	v_fmac_f32_e32 v18, v169, v23
	v_max_f32_e32 v25, 0, v25
	v_fmac_f32_e32 v18, v168, v24
	v_max_f32_e32 v26, 0, v26
	v_fmac_f32_e32 v18, v167, v25
	v_max_f32_e32 v27, 0, v27
	v_fmac_f32_e32 v18, v166, v26
	v_max_f32_e32 v28, 0, v28
	v_fmac_f32_e32 v18, v165, v27
	v_max_f32_e32 v29, 0, v29
	v_fmac_f32_e32 v18, v164, v28
	v_max_f32_e32 v30, 0, v30
	v_fmac_f32_e32 v18, v163, v29
	v_fmac_f32_e32 v18, v162, v30
	v_max_f32_e32 v19, 0, v31
	v_fmac_f32_e32 v18, v161, v19
	v_max_f32_e32 v19, 0, v32
	v_fmac_f32_e32 v18, v160, v19
	v_max_f32_e32 v19, 0, v33
	v_fmac_f32_e32 v18, v89, v19
	v_not_b32_e32 v19, v18
	v_or_b32_e32 v20, 0x80000000, v18
	v_cmp_gt_i32_e32 vcc, 0, v18
	s_nop 1
	v_cndmask_b32_e32 v18, v20, v19, vcc
	v_cmp_le_u32_e32 vcc, v102, v87
	s_nop 1
	v_cndmask_b32_e32 v183, 0, v18, vcc

.LBB0_432:
	s_or_b64 exec, exec, s[84:85]
	v_mfma_f32_32x32x16_bf16 v[18:33], v[38:41], v[58:61], 0
	v_mfma_f32_32x32x16_bf16 v[18:33], v[46:49], v[54:57], v[18:33]
	v_mfma_f32_32x32x16_bf16 v[18:33], v[34:37], v[50:53], v[18:33]
	v_mfma_f32_32x32x16_bf16 v[18:33], v[42:45], v[62:65], v[18:33]
	s_waitcnt vmcnt(12)
	ds_read_b128 v[58:61], v74 offset:4096
	ds_read_b128 v[54:57], v75 offset:4096
	ds_read_b128 v[50:53], v76 offset:4096
	ds_read_b128 v[62:65], v77 offset:4096
	s_nop 8
	v_max_f32_e32 v18, 0, v18
	v_max_f32_e32 v19, 0, v19
	v_fma_f32 v18, v174, v18, 0
	v_max_f32_e32 v20, 0, v20
	v_fmac_f32_e32 v18, v173, v19
	v_max_f32_e32 v21, 0, v21
	v_fmac_f32_e32 v18, v172, v20
	v_max_f32_e32 v22, 0, v22
	v_fmac_f32_e32 v18, v171, v21
	v_max_f32_e32 v23, 0, v23
	v_fmac_f32_e32 v18, v170, v22
	v_max_f32_e32 v24, 0, v24
	v_fmac_f32_e32 v18, v169, v23
	v_max_f32_e32 v25, 0, v25
	v_fmac_f32_e32 v18, v168, v24
	v_max_f32_e32 v26, 0, v26
	v_fmac_f32_e32 v18, v167, v25
	v_max_f32_e32 v27, 0, v27
	v_fmac_f32_e32 v18, v166, v26
	v_max_f32_e32 v28, 0, v28
	v_fmac_f32_e32 v18, v165, v27
	v_max_f32_e32 v29, 0, v29
	v_fmac_f32_e32 v18, v164, v28
	v_max_f32_e32 v30, 0, v30
	v_fmac_f32_e32 v18, v163, v29
	v_fmac_f32_e32 v18, v162, v30
	v_max_f32_e32 v19, 0, v31
	v_fmac_f32_e32 v18, v161, v19
	v_max_f32_e32 v19, 0, v32
	v_fmac_f32_e32 v18, v160, v19
	v_max_f32_e32 v19, 0, v33
	v_fmac_f32_e32 v18, v89, v19
	v_not_b32_e32 v19, v18
	v_or_b32_e32 v20, 0x80000000, v18
	v_cmp_gt_i32_e32 vcc, 0, v18
	s_nop 1
	v_cndmask_b32_e32 v18, v20, v19, vcc
	v_cmp_le_u32_e32 vcc, v103, v87
	s_nop 1
	v_cndmask_b32_e32 v184, 0, v18, vcc

.LBB0_436:
	s_or_b64 exec, exec, s[84:85]
	v_mfma_f32_32x32x16_bf16 v[18:33], v[38:41], v[58:61], 0
	v_mfma_f32_32x32x16_bf16 v[18:33], v[46:49], v[54:57], v[18:33]
	v_mfma_f32_32x32x16_bf16 v[18:33], v[34:37], v[50:53], v[18:33]
	v_mfma_f32_32x32x16_bf16 v[18:33], v[42:45], v[62:65], v[18:33]
	s_waitcnt vmcnt(12)
	ds_read_b128 v[58:61], v74 offset:8192
	ds_read_b128 v[54:57], v75 offset:8192
	ds_read_b128 v[50:53], v76 offset:8192
	ds_read_b128 v[62:65], v77 offset:8192
	s_nop 8
	v_max_f32_e32 v18, 0, v18
	v_max_f32_e32 v19, 0, v19
	v_fma_f32 v18, v174, v18, 0
	v_max_f32_e32 v20, 0, v20
	v_fmac_f32_e32 v18, v173, v19
	v_max_f32_e32 v21, 0, v21
	v_fmac_f32_e32 v18, v172, v20
	v_max_f32_e32 v22, 0, v22
	v_fmac_f32_e32 v18, v171, v21
	v_max_f32_e32 v23, 0, v23
	v_fmac_f32_e32 v18, v170, v22
	v_max_f32_e32 v24, 0, v24
	v_fmac_f32_e32 v18, v169, v23
	v_max_f32_e32 v25, 0, v25
	v_fmac_f32_e32 v18, v168, v24
	v_max_f32_e32 v26, 0, v26
	v_fmac_f32_e32 v18, v167, v25
	v_max_f32_e32 v27, 0, v27
	v_fmac_f32_e32 v18, v166, v26
	v_max_f32_e32 v28, 0, v28
	v_fmac_f32_e32 v18, v165, v27
	v_max_f32_e32 v29, 0, v29
	v_fmac_f32_e32 v18, v164, v28
	v_max_f32_e32 v30, 0, v30
	v_fmac_f32_e32 v18, v163, v29
	v_fmac_f32_e32 v18, v162, v30
	v_max_f32_e32 v19, 0, v31
	v_fmac_f32_e32 v18, v161, v19
	v_max_f32_e32 v19, 0, v32
	v_fmac_f32_e32 v18, v160, v19
	v_max_f32_e32 v19, 0, v33
	v_fmac_f32_e32 v18, v89, v19
	v_not_b32_e32 v19, v18
	v_or_b32_e32 v20, 0x80000000, v18
	v_cmp_gt_i32_e32 vcc, 0, v18
	s_nop 1
	v_cndmask_b32_e32 v18, v20, v19, vcc
	v_cmp_le_u32_e32 vcc, v104, v87
	s_nop 1
	v_cndmask_b32_e32 v185, 0, v18, vcc

.LBB0_440:
	s_or_b64 exec, exec, s[84:85]
	v_mfma_f32_32x32x16_bf16 v[18:33], v[38:41], v[58:61], 0
	v_mfma_f32_32x32x16_bf16 v[18:33], v[46:49], v[54:57], v[18:33]
	v_mfma_f32_32x32x16_bf16 v[18:33], v[34:37], v[50:53], v[18:33]
	v_mfma_f32_32x32x16_bf16 v[18:33], v[42:45], v[62:65], v[18:33]
	s_waitcnt vmcnt(12)
	ds_read_b128 v[58:61], v74 offset:12288
	ds_read_b128 v[54:57], v75 offset:12288
	ds_read_b128 v[50:53], v76 offset:12288
	ds_read_b128 v[62:65], v77 offset:12288
	s_nop 8
	v_max_f32_e32 v18, 0, v18
	v_max_f32_e32 v19, 0, v19
	v_fma_f32 v18, v174, v18, 0
	v_max_f32_e32 v20, 0, v20
	v_fmac_f32_e32 v18, v173, v19
	v_max_f32_e32 v21, 0, v21
	v_fmac_f32_e32 v18, v172, v20
	v_max_f32_e32 v22, 0, v22
	v_fmac_f32_e32 v18, v171, v21
	v_max_f32_e32 v23, 0, v23
	v_fmac_f32_e32 v18, v170, v22
	v_max_f32_e32 v24, 0, v24
	v_fmac_f32_e32 v18, v169, v23
	v_max_f32_e32 v25, 0, v25
	v_fmac_f32_e32 v18, v168, v24
	v_max_f32_e32 v26, 0, v26
	v_fmac_f32_e32 v18, v167, v25
	v_max_f32_e32 v27, 0, v27
	v_fmac_f32_e32 v18, v166, v26
	v_max_f32_e32 v28, 0, v28
	v_fmac_f32_e32 v18, v165, v27
	v_max_f32_e32 v29, 0, v29
	v_fmac_f32_e32 v18, v164, v28
	v_max_f32_e32 v30, 0, v30
	v_fmac_f32_e32 v18, v163, v29
	v_fmac_f32_e32 v18, v162, v30
	v_max_f32_e32 v19, 0, v31
	v_fmac_f32_e32 v18, v161, v19
	v_max_f32_e32 v19, 0, v32
	v_fmac_f32_e32 v18, v160, v19
	v_max_f32_e32 v19, 0, v33
	v_fmac_f32_e32 v18, v89, v19
	v_not_b32_e32 v19, v18
	v_or_b32_e32 v20, 0x80000000, v18
	v_cmp_gt_i32_e32 vcc, 0, v18
	s_nop 1
	v_cndmask_b32_e32 v18, v20, v19, vcc
	v_cmp_le_u32_e32 vcc, v105, v87
	s_nop 1
	v_cndmask_b32_e32 v186, 0, v18, vcc

.LBB0_444:
	s_or_b64 exec, exec, s[84:85]
	v_mfma_f32_32x32x16_bf16 v[18:33], v[38:41], v[58:61], 0
	v_mfma_f32_32x32x16_bf16 v[18:33], v[46:49], v[54:57], v[18:33]
	v_mfma_f32_32x32x16_bf16 v[18:33], v[34:37], v[50:53], v[18:33]
	v_mfma_f32_32x32x16_bf16 v[18:33], v[42:45], v[62:65], v[18:33]
	s_waitcnt vmcnt(12)
	ds_read_b128 v[58:61], v74 offset:0
	ds_read_b128 v[54:57], v75 offset:0
	ds_read_b128 v[50:53], v76 offset:0
	ds_read_b128 v[62:65], v77 offset:0
	s_nop 8
	v_max_f32_e32 v18, 0, v18
	v_max_f32_e32 v19, 0, v19
	v_fma_f32 v18, v174, v18, 0
	v_max_f32_e32 v20, 0, v20
	v_fmac_f32_e32 v18, v173, v19
	v_max_f32_e32 v21, 0, v21
	v_fmac_f32_e32 v18, v172, v20
	v_max_f32_e32 v22, 0, v22
	v_fmac_f32_e32 v18, v171, v21
	v_max_f32_e32 v23, 0, v23
	v_fmac_f32_e32 v18, v170, v22
	v_max_f32_e32 v24, 0, v24
	v_fmac_f32_e32 v18, v169, v23
	v_max_f32_e32 v25, 0, v25
	v_fmac_f32_e32 v18, v168, v24
	v_max_f32_e32 v26, 0, v26
	v_fmac_f32_e32 v18, v167, v25
	v_max_f32_e32 v27, 0, v27
	v_fmac_f32_e32 v18, v166, v26
	v_max_f32_e32 v28, 0, v28
	v_fmac_f32_e32 v18, v165, v27
	v_max_f32_e32 v29, 0, v29
	v_fmac_f32_e32 v18, v164, v28
	v_max_f32_e32 v30, 0, v30
	v_fmac_f32_e32 v18, v163, v29
	v_fmac_f32_e32 v18, v162, v30
	v_max_f32_e32 v19, 0, v31
	v_fmac_f32_e32 v18, v161, v19
	v_max_f32_e32 v19, 0, v32
	v_fmac_f32_e32 v18, v160, v19
	v_max_f32_e32 v19, 0, v33
	v_fmac_f32_e32 v18, v89, v19
	v_not_b32_e32 v19, v18
	v_or_b32_e32 v20, 0x80000000, v18
	v_cmp_gt_i32_e32 vcc, 0, v18
	s_nop 1
	v_cndmask_b32_e32 v18, v20, v19, vcc
	v_cmp_le_u32_e32 vcc, v106, v87
	s_nop 1
	v_cndmask_b32_e32 v187, 0, v18, vcc

.LBB0_448:
	s_or_b64 exec, exec, s[84:85]
	v_mfma_f32_32x32x16_bf16 v[18:33], v[38:41], v[58:61], 0
	v_mfma_f32_32x32x16_bf16 v[18:33], v[46:49], v[54:57], v[18:33]
	v_mfma_f32_32x32x16_bf16 v[18:33], v[34:37], v[50:53], v[18:33]
	v_mfma_f32_32x32x16_bf16 v[18:33], v[42:45], v[62:65], v[18:33]
	s_waitcnt vmcnt(12)
	ds_read_b128 v[58:61], v74 offset:4096
	ds_read_b128 v[54:57], v75 offset:4096
	ds_read_b128 v[50:53], v76 offset:4096
	ds_read_b128 v[62:65], v77 offset:4096
	s_nop 8
	v_max_f32_e32 v18, 0, v18
	v_max_f32_e32 v19, 0, v19
	v_fma_f32 v18, v174, v18, 0
	v_max_f32_e32 v20, 0, v20
	v_fmac_f32_e32 v18, v173, v19
	v_max_f32_e32 v21, 0, v21
	v_fmac_f32_e32 v18, v172, v20
	v_max_f32_e32 v22, 0, v22
	v_fmac_f32_e32 v18, v171, v21
	v_max_f32_e32 v23, 0, v23
	v_fmac_f32_e32 v18, v170, v22
	v_max_f32_e32 v24, 0, v24
	v_fmac_f32_e32 v18, v169, v23
	v_max_f32_e32 v25, 0, v25
	v_fmac_f32_e32 v18, v168, v24
	v_max_f32_e32 v26, 0, v26
	v_fmac_f32_e32 v18, v167, v25
	v_max_f32_e32 v27, 0, v27
	v_fmac_f32_e32 v18, v166, v26
	v_max_f32_e32 v28, 0, v28
	v_fmac_f32_e32 v18, v165, v27
	v_max_f32_e32 v29, 0, v29
	v_fmac_f32_e32 v18, v164, v28
	v_max_f32_e32 v30, 0, v30
	v_fmac_f32_e32 v18, v163, v29
	v_fmac_f32_e32 v18, v162, v30
	v_max_f32_e32 v19, 0, v31
	v_fmac_f32_e32 v18, v161, v19
	v_max_f32_e32 v19, 0, v32
	v_fmac_f32_e32 v18, v160, v19
	v_max_f32_e32 v19, 0, v33
	v_fmac_f32_e32 v18, v89, v19
	v_not_b32_e32 v19, v18
	v_or_b32_e32 v20, 0x80000000, v18
	v_cmp_gt_i32_e32 vcc, 0, v18
	s_nop 1
	v_cndmask_b32_e32 v18, v20, v19, vcc
	v_cmp_le_u32_e32 vcc, v107, v87
	s_nop 1
	v_cndmask_b32_e32 v188, 0, v18, vcc

.LBB0_452:
	s_or_b64 exec, exec, s[84:85]
	v_mfma_f32_32x32x16_bf16 v[18:33], v[38:41], v[58:61], 0
	v_mfma_f32_32x32x16_bf16 v[18:33], v[46:49], v[54:57], v[18:33]
	v_mfma_f32_32x32x16_bf16 v[18:33], v[34:37], v[50:53], v[18:33]
	v_mfma_f32_32x32x16_bf16 v[18:33], v[42:45], v[62:65], v[18:33]
	s_waitcnt vmcnt(12)
	ds_read_b128 v[58:61], v74 offset:8192
	ds_read_b128 v[54:57], v75 offset:8192
	ds_read_b128 v[50:53], v76 offset:8192
	ds_read_b128 v[62:65], v77 offset:8192
	s_nop 8
	v_max_f32_e32 v18, 0, v18
	v_max_f32_e32 v19, 0, v19
	v_fma_f32 v18, v174, v18, 0
	v_max_f32_e32 v20, 0, v20
	v_fmac_f32_e32 v18, v173, v19
	v_max_f32_e32 v21, 0, v21
	v_fmac_f32_e32 v18, v172, v20
	v_max_f32_e32 v22, 0, v22
	v_fmac_f32_e32 v18, v171, v21
	v_max_f32_e32 v23, 0, v23
	v_fmac_f32_e32 v18, v170, v22
	v_max_f32_e32 v24, 0, v24
	v_fmac_f32_e32 v18, v169, v23
	v_max_f32_e32 v25, 0, v25
	v_fmac_f32_e32 v18, v168, v24
	v_max_f32_e32 v26, 0, v26
	v_fmac_f32_e32 v18, v167, v25
	v_max_f32_e32 v27, 0, v27
	v_fmac_f32_e32 v18, v166, v26
	v_max_f32_e32 v28, 0, v28
	v_fmac_f32_e32 v18, v165, v27
	v_max_f32_e32 v29, 0, v29
	v_fmac_f32_e32 v18, v164, v28
	v_max_f32_e32 v30, 0, v30
	v_fmac_f32_e32 v18, v163, v29
	v_fmac_f32_e32 v18, v162, v30
	v_max_f32_e32 v19, 0, v31
	v_fmac_f32_e32 v18, v161, v19
	v_max_f32_e32 v19, 0, v32
	v_fmac_f32_e32 v18, v160, v19
	v_max_f32_e32 v19, 0, v33
	v_fmac_f32_e32 v18, v89, v19
	v_not_b32_e32 v19, v18
	v_or_b32_e32 v20, 0x80000000, v18
	v_cmp_gt_i32_e32 vcc, 0, v18
	s_nop 1
	v_cndmask_b32_e32 v18, v20, v19, vcc
	v_cmp_le_u32_e32 vcc, v108, v87
	s_nop 1
	v_cndmask_b32_e32 v189, 0, v18, vcc

.LBB0_456:
	s_or_b64 exec, exec, s[84:85]
	v_mfma_f32_32x32x16_bf16 v[18:33], v[38:41], v[58:61], 0
	v_mfma_f32_32x32x16_bf16 v[18:33], v[46:49], v[54:57], v[18:33]
	v_mfma_f32_32x32x16_bf16 v[18:33], v[34:37], v[50:53], v[18:33]
	v_mfma_f32_32x32x16_bf16 v[18:33], v[42:45], v[62:65], v[18:33]
	s_waitcnt vmcnt(12)
	ds_read_b128 v[58:61], v74 offset:12288
	ds_read_b128 v[54:57], v75 offset:12288
	ds_read_b128 v[50:53], v76 offset:12288
	ds_read_b128 v[62:65], v77 offset:12288
	s_nop 8
	v_max_f32_e32 v18, 0, v18
	v_max_f32_e32 v19, 0, v19
	v_fma_f32 v18, v174, v18, 0
	v_max_f32_e32 v20, 0, v20
	v_fmac_f32_e32 v18, v173, v19
	v_max_f32_e32 v21, 0, v21
	v_fmac_f32_e32 v18, v172, v20
	v_max_f32_e32 v22, 0, v22
	v_fmac_f32_e32 v18, v171, v21
	v_max_f32_e32 v23, 0, v23
	v_fmac_f32_e32 v18, v170, v22
	v_max_f32_e32 v24, 0, v24
	v_fmac_f32_e32 v18, v169, v23
	v_max_f32_e32 v25, 0, v25
	v_fmac_f32_e32 v18, v168, v24
	v_max_f32_e32 v26, 0, v26
	v_fmac_f32_e32 v18, v167, v25
	v_max_f32_e32 v27, 0, v27
	v_fmac_f32_e32 v18, v166, v26
	v_max_f32_e32 v28, 0, v28
	v_fmac_f32_e32 v18, v165, v27
	v_max_f32_e32 v29, 0, v29
	v_fmac_f32_e32 v18, v164, v28
	v_max_f32_e32 v30, 0, v30
	v_fmac_f32_e32 v18, v163, v29
	v_fmac_f32_e32 v18, v162, v30
	v_max_f32_e32 v19, 0, v31
	v_fmac_f32_e32 v18, v161, v19
	v_max_f32_e32 v19, 0, v32
	v_fmac_f32_e32 v18, v160, v19
	v_max_f32_e32 v19, 0, v33
	v_fmac_f32_e32 v18, v89, v19
	v_not_b32_e32 v19, v18
	v_or_b32_e32 v20, 0x80000000, v18
	v_cmp_gt_i32_e32 vcc, 0, v18
	s_nop 1
	v_cndmask_b32_e32 v18, v20, v19, vcc
	v_cmp_le_u32_e32 vcc, v109, v87
	s_nop 1
	v_cndmask_b32_e32 v190, 0, v18, vcc

.LBB0_460:
	s_or_b64 exec, exec, s[84:85]
	v_mfma_f32_32x32x16_bf16 v[18:33], v[38:41], v[58:61], 0
	v_mfma_f32_32x32x16_bf16 v[18:33], v[46:49], v[54:57], v[18:33]
	v_mfma_f32_32x32x16_bf16 v[18:33], v[34:37], v[50:53], v[18:33]
	v_mfma_f32_32x32x16_bf16 v[18:33], v[42:45], v[62:65], v[18:33]
	s_waitcnt vmcnt(12)
	ds_read_b128 v[58:61], v74 offset:0
	ds_read_b128 v[54:57], v75 offset:0
	ds_read_b128 v[50:53], v76 offset:0
	ds_read_b128 v[62:65], v77 offset:0
	s_nop 8
	v_max_f32_e32 v18, 0, v18
	v_max_f32_e32 v19, 0, v19
	v_fma_f32 v18, v174, v18, 0
	v_max_f32_e32 v20, 0, v20
	v_fmac_f32_e32 v18, v173, v19
	v_max_f32_e32 v21, 0, v21
	v_fmac_f32_e32 v18, v172, v20
	v_max_f32_e32 v22, 0, v22
	v_fmac_f32_e32 v18, v171, v21
	v_max_f32_e32 v23, 0, v23
	v_fmac_f32_e32 v18, v170, v22
	v_max_f32_e32 v24, 0, v24
	v_fmac_f32_e32 v18, v169, v23
	v_max_f32_e32 v25, 0, v25
	v_fmac_f32_e32 v18, v168, v24
	v_max_f32_e32 v26, 0, v26
	v_fmac_f32_e32 v18, v167, v25
	v_max_f32_e32 v27, 0, v27
	v_fmac_f32_e32 v18, v166, v26
	v_max_f32_e32 v28, 0, v28
	v_fmac_f32_e32 v18, v165, v27
	v_max_f32_e32 v29, 0, v29
	v_fmac_f32_e32 v18, v164, v28
	v_max_f32_e32 v30, 0, v30
	v_fmac_f32_e32 v18, v163, v29
	v_fmac_f32_e32 v18, v162, v30
	v_max_f32_e32 v19, 0, v31
	v_fmac_f32_e32 v18, v161, v19
	v_max_f32_e32 v19, 0, v32
	v_fmac_f32_e32 v18, v160, v19
	v_max_f32_e32 v19, 0, v33
	v_fmac_f32_e32 v18, v89, v19
	v_not_b32_e32 v19, v18
	v_or_b32_e32 v20, 0x80000000, v18
	v_cmp_gt_i32_e32 vcc, 0, v18
	s_nop 1
	v_cndmask_b32_e32 v18, v20, v19, vcc
	v_cmp_le_u32_e32 vcc, v110, v87
	s_nop 1
	v_cndmask_b32_e32 v191, 0, v18, vcc

.LBB0_464:
	s_or_b64 exec, exec, s[84:85]
	v_mfma_f32_32x32x16_bf16 v[18:33], v[38:41], v[58:61], 0
	v_mfma_f32_32x32x16_bf16 v[18:33], v[46:49], v[54:57], v[18:33]
	v_mfma_f32_32x32x16_bf16 v[18:33], v[34:37], v[50:53], v[18:33]
	v_mfma_f32_32x32x16_bf16 v[18:33], v[42:45], v[62:65], v[18:33]
	s_waitcnt vmcnt(12)
	ds_read_b128 v[58:61], v74 offset:4096
	ds_read_b128 v[54:57], v75 offset:4096
	ds_read_b128 v[50:53], v76 offset:4096
	ds_read_b128 v[62:65], v77 offset:4096
	s_nop 8
	v_max_f32_e32 v18, 0, v18
	v_max_f32_e32 v19, 0, v19
	v_fma_f32 v18, v174, v18, 0
	v_max_f32_e32 v20, 0, v20
	v_fmac_f32_e32 v18, v173, v19
	v_max_f32_e32 v21, 0, v21
	v_fmac_f32_e32 v18, v172, v20
	v_max_f32_e32 v22, 0, v22
	v_fmac_f32_e32 v18, v171, v21
	v_max_f32_e32 v23, 0, v23
	v_fmac_f32_e32 v18, v170, v22
	v_max_f32_e32 v24, 0, v24
	v_fmac_f32_e32 v18, v169, v23
	v_max_f32_e32 v25, 0, v25
	v_fmac_f32_e32 v18, v168, v24
	v_max_f32_e32 v26, 0, v26
	v_fmac_f32_e32 v18, v167, v25
	v_max_f32_e32 v27, 0, v27
	v_fmac_f32_e32 v18, v166, v26
	v_max_f32_e32 v28, 0, v28
	v_fmac_f32_e32 v18, v165, v27
	v_max_f32_e32 v29, 0, v29
	v_fmac_f32_e32 v18, v164, v28
	v_max_f32_e32 v30, 0, v30
	v_fmac_f32_e32 v18, v163, v29
	v_fmac_f32_e32 v18, v162, v30
	v_max_f32_e32 v19, 0, v31
	v_fmac_f32_e32 v18, v161, v19
	v_max_f32_e32 v19, 0, v32
	v_fmac_f32_e32 v18, v160, v19
	v_max_f32_e32 v19, 0, v33
	v_fmac_f32_e32 v18, v89, v19
	v_not_b32_e32 v19, v18
	v_or_b32_e32 v20, 0x80000000, v18
	v_cmp_gt_i32_e32 vcc, 0, v18
	s_nop 1
	v_cndmask_b32_e32 v18, v20, v19, vcc
	v_cmp_le_u32_e32 vcc, v111, v87
	s_nop 1
	v_cndmask_b32_e32 v192, 0, v18, vcc

.LBB0_468:
	s_or_b64 exec, exec, s[84:85]
	v_mfma_f32_32x32x16_bf16 v[18:33], v[38:41], v[58:61], 0
	v_mfma_f32_32x32x16_bf16 v[18:33], v[46:49], v[54:57], v[18:33]
	v_mfma_f32_32x32x16_bf16 v[18:33], v[34:37], v[50:53], v[18:33]
	v_mfma_f32_32x32x16_bf16 v[18:33], v[42:45], v[62:65], v[18:33]
	s_waitcnt vmcnt(12)
	ds_read_b128 v[58:61], v74 offset:8192
	ds_read_b128 v[54:57], v75 offset:8192
	ds_read_b128 v[50:53], v76 offset:8192
	ds_read_b128 v[62:65], v77 offset:8192
	s_nop 8
	v_max_f32_e32 v18, 0, v18
	v_max_f32_e32 v19, 0, v19
	v_fma_f32 v18, v174, v18, 0
	v_max_f32_e32 v20, 0, v20
	v_fmac_f32_e32 v18, v173, v19
	v_max_f32_e32 v21, 0, v21
	v_fmac_f32_e32 v18, v172, v20
	v_max_f32_e32 v22, 0, v22
	v_fmac_f32_e32 v18, v171, v21
	v_max_f32_e32 v23, 0, v23
	v_fmac_f32_e32 v18, v170, v22
	v_max_f32_e32 v24, 0, v24
	v_fmac_f32_e32 v18, v169, v23
	v_max_f32_e32 v25, 0, v25
	v_fmac_f32_e32 v18, v168, v24
	v_max_f32_e32 v26, 0, v26
	v_fmac_f32_e32 v18, v167, v25
	v_max_f32_e32 v27, 0, v27
	v_fmac_f32_e32 v18, v166, v26
	v_max_f32_e32 v28, 0, v28
	v_fmac_f32_e32 v18, v165, v27
	v_max_f32_e32 v29, 0, v29
	v_fmac_f32_e32 v18, v164, v28
	v_max_f32_e32 v30, 0, v30
	v_fmac_f32_e32 v18, v163, v29
	v_fmac_f32_e32 v18, v162, v30
	v_max_f32_e32 v19, 0, v31
	v_fmac_f32_e32 v18, v161, v19
	v_max_f32_e32 v19, 0, v32
	v_fmac_f32_e32 v18, v160, v19
	v_max_f32_e32 v19, 0, v33
	v_fmac_f32_e32 v18, v89, v19
	v_not_b32_e32 v19, v18
	v_or_b32_e32 v20, 0x80000000, v18
	v_cmp_gt_i32_e32 vcc, 0, v18
	s_nop 1
	v_cndmask_b32_e32 v18, v20, v19, vcc
	v_cmp_le_u32_e32 vcc, v112, v87
	s_nop 1
	v_cndmask_b32_e32 v193, 0, v18, vcc

.LBB0_472:
	s_or_b64 exec, exec, s[84:85]
	v_mfma_f32_32x32x16_bf16 v[18:33], v[38:41], v[58:61], 0
	v_mfma_f32_32x32x16_bf16 v[18:33], v[46:49], v[54:57], v[18:33]
	v_mfma_f32_32x32x16_bf16 v[18:33], v[34:37], v[50:53], v[18:33]
	v_mfma_f32_32x32x16_bf16 v[18:33], v[42:45], v[62:65], v[18:33]
	s_waitcnt vmcnt(12)
	ds_read_b128 v[58:61], v74 offset:12288
	ds_read_b128 v[54:57], v75 offset:12288
	ds_read_b128 v[50:53], v76 offset:12288
	ds_read_b128 v[62:65], v77 offset:12288
	s_nop 8
	v_max_f32_e32 v18, 0, v18
	v_max_f32_e32 v19, 0, v19
	v_fma_f32 v18, v174, v18, 0
	v_max_f32_e32 v20, 0, v20
	v_fmac_f32_e32 v18, v173, v19
	v_max_f32_e32 v21, 0, v21
	v_fmac_f32_e32 v18, v172, v20
	v_max_f32_e32 v22, 0, v22
	v_fmac_f32_e32 v18, v171, v21
	v_max_f32_e32 v23, 0, v23
	v_fmac_f32_e32 v18, v170, v22
	v_max_f32_e32 v24, 0, v24
	v_fmac_f32_e32 v18, v169, v23
	v_max_f32_e32 v25, 0, v25
	v_fmac_f32_e32 v18, v168, v24
	v_max_f32_e32 v26, 0, v26
	v_fmac_f32_e32 v18, v167, v25
	v_max_f32_e32 v27, 0, v27
	v_fmac_f32_e32 v18, v166, v26
	v_max_f32_e32 v28, 0, v28
	v_fmac_f32_e32 v18, v165, v27
	v_max_f32_e32 v29, 0, v29
	v_fmac_f32_e32 v18, v164, v28
	v_max_f32_e32 v30, 0, v30
	v_fmac_f32_e32 v18, v163, v29
	v_fmac_f32_e32 v18, v162, v30
	v_max_f32_e32 v19, 0, v31
	v_fmac_f32_e32 v18, v161, v19
	v_max_f32_e32 v19, 0, v32
	v_fmac_f32_e32 v18, v160, v19
	v_max_f32_e32 v19, 0, v33
	v_fmac_f32_e32 v18, v89, v19
	v_not_b32_e32 v19, v18
	v_or_b32_e32 v20, 0x80000000, v18
	v_cmp_gt_i32_e32 vcc, 0, v18
	s_nop 1
	v_cndmask_b32_e32 v18, v20, v19, vcc
	v_cmp_le_u32_e32 vcc, v113, v87
	s_nop 1
	v_cndmask_b32_e32 v194, 0, v18, vcc

.LBB0_476:
	s_or_b64 exec, exec, s[84:85]
	v_mfma_f32_32x32x16_bf16 v[18:33], v[38:41], v[58:61], 0
	v_mfma_f32_32x32x16_bf16 v[18:33], v[46:49], v[54:57], v[18:33]
	v_mfma_f32_32x32x16_bf16 v[18:33], v[34:37], v[50:53], v[18:33]
	v_mfma_f32_32x32x16_bf16 v[18:33], v[42:45], v[62:65], v[18:33]
	s_waitcnt vmcnt(12)
	ds_read_b128 v[58:61], v74 offset:0
	ds_read_b128 v[54:57], v75 offset:0
	ds_read_b128 v[50:53], v76 offset:0
	ds_read_b128 v[62:65], v77 offset:0
	s_nop 8
	v_max_f32_e32 v18, 0, v18
	v_max_f32_e32 v19, 0, v19
	v_fma_f32 v18, v174, v18, 0
	v_max_f32_e32 v20, 0, v20
	v_fmac_f32_e32 v18, v173, v19
	v_max_f32_e32 v21, 0, v21
	v_fmac_f32_e32 v18, v172, v20
	v_max_f32_e32 v22, 0, v22
	v_fmac_f32_e32 v18, v171, v21
	v_max_f32_e32 v23, 0, v23
	v_fmac_f32_e32 v18, v170, v22
	v_max_f32_e32 v24, 0, v24
	v_fmac_f32_e32 v18, v169, v23
	v_max_f32_e32 v25, 0, v25
	v_fmac_f32_e32 v18, v168, v24
	v_max_f32_e32 v26, 0, v26
	v_fmac_f32_e32 v18, v167, v25
	v_max_f32_e32 v27, 0, v27
	v_fmac_f32_e32 v18, v166, v26
	v_max_f32_e32 v28, 0, v28
	v_fmac_f32_e32 v18, v165, v27
	v_max_f32_e32 v29, 0, v29
	v_fmac_f32_e32 v18, v164, v28
	v_max_f32_e32 v30, 0, v30
	v_fmac_f32_e32 v18, v163, v29
	v_fmac_f32_e32 v18, v162, v30
	v_max_f32_e32 v19, 0, v31
	v_fmac_f32_e32 v18, v161, v19
	v_max_f32_e32 v19, 0, v32
	v_fmac_f32_e32 v18, v160, v19
	v_max_f32_e32 v19, 0, v33
	v_fmac_f32_e32 v18, v89, v19
	v_not_b32_e32 v19, v18
	v_or_b32_e32 v20, 0x80000000, v18
	v_cmp_gt_i32_e32 vcc, 0, v18
	s_nop 1
	v_cndmask_b32_e32 v18, v20, v19, vcc
	v_cmp_le_u32_e32 vcc, v114, v87
	s_nop 1
	v_cndmask_b32_e32 v195, 0, v18, vcc

.LBB0_480:
	s_or_b64 exec, exec, s[84:85]
	v_mfma_f32_32x32x16_bf16 v[18:33], v[38:41], v[58:61], 0
	v_mfma_f32_32x32x16_bf16 v[18:33], v[46:49], v[54:57], v[18:33]
	v_mfma_f32_32x32x16_bf16 v[18:33], v[34:37], v[50:53], v[18:33]
	v_mfma_f32_32x32x16_bf16 v[18:33], v[42:45], v[62:65], v[18:33]
	s_waitcnt vmcnt(12)
	ds_read_b128 v[58:61], v74 offset:4096
	ds_read_b128 v[54:57], v75 offset:4096
	ds_read_b128 v[50:53], v76 offset:4096
	ds_read_b128 v[62:65], v77 offset:4096
	s_nop 8
	v_max_f32_e32 v18, 0, v18
	v_max_f32_e32 v19, 0, v19
	v_fma_f32 v18, v174, v18, 0
	v_max_f32_e32 v20, 0, v20
	v_fmac_f32_e32 v18, v173, v19
	v_max_f32_e32 v21, 0, v21
	v_fmac_f32_e32 v18, v172, v20
	v_max_f32_e32 v22, 0, v22
	v_fmac_f32_e32 v18, v171, v21
	v_max_f32_e32 v23, 0, v23
	v_fmac_f32_e32 v18, v170, v22
	v_max_f32_e32 v24, 0, v24
	v_fmac_f32_e32 v18, v169, v23
	v_max_f32_e32 v25, 0, v25
	v_fmac_f32_e32 v18, v168, v24
	v_max_f32_e32 v26, 0, v26
	v_fmac_f32_e32 v18, v167, v25
	v_max_f32_e32 v27, 0, v27
	v_fmac_f32_e32 v18, v166, v26
	v_max_f32_e32 v28, 0, v28
	v_fmac_f32_e32 v18, v165, v27
	v_max_f32_e32 v29, 0, v29
	v_fmac_f32_e32 v18, v164, v28
	v_max_f32_e32 v30, 0, v30
	v_fmac_f32_e32 v18, v163, v29
	v_fmac_f32_e32 v18, v162, v30
	v_max_f32_e32 v19, 0, v31
	v_fmac_f32_e32 v18, v161, v19
	v_max_f32_e32 v19, 0, v32
	v_fmac_f32_e32 v18, v160, v19
	v_max_f32_e32 v19, 0, v33
	v_fmac_f32_e32 v18, v89, v19
	v_not_b32_e32 v19, v18
	v_or_b32_e32 v20, 0x80000000, v18
	v_cmp_gt_i32_e32 vcc, 0, v18
	s_nop 1
	v_cndmask_b32_e32 v18, v20, v19, vcc
	v_cmp_le_u32_e32 vcc, v115, v87
	s_nop 1
	v_cndmask_b32_e32 v196, 0, v18, vcc

.LBB0_484:
	s_or_b64 exec, exec, s[84:85]
	v_mfma_f32_32x32x16_bf16 v[18:33], v[38:41], v[58:61], 0
	v_mfma_f32_32x32x16_bf16 v[18:33], v[46:49], v[54:57], v[18:33]
	v_mfma_f32_32x32x16_bf16 v[18:33], v[34:37], v[50:53], v[18:33]
	v_mfma_f32_32x32x16_bf16 v[18:33], v[42:45], v[62:65], v[18:33]
	s_waitcnt vmcnt(12)
	ds_read_b128 v[58:61], v74 offset:8192
	ds_read_b128 v[54:57], v75 offset:8192
	ds_read_b128 v[50:53], v76 offset:8192
	ds_read_b128 v[62:65], v77 offset:8192
	s_nop 8
	v_max_f32_e32 v18, 0, v18
	v_max_f32_e32 v19, 0, v19
	v_fma_f32 v18, v174, v18, 0
	v_max_f32_e32 v20, 0, v20
	v_fmac_f32_e32 v18, v173, v19
	v_max_f32_e32 v21, 0, v21
	v_fmac_f32_e32 v18, v172, v20
	v_max_f32_e32 v22, 0, v22
	v_fmac_f32_e32 v18, v171, v21
	v_max_f32_e32 v23, 0, v23
	v_fmac_f32_e32 v18, v170, v22
	v_max_f32_e32 v24, 0, v24
	v_fmac_f32_e32 v18, v169, v23
	v_max_f32_e32 v25, 0, v25
	v_fmac_f32_e32 v18, v168, v24
	v_max_f32_e32 v26, 0, v26
	v_fmac_f32_e32 v18, v167, v25
	v_max_f32_e32 v27, 0, v27
	v_fmac_f32_e32 v18, v166, v26
	v_max_f32_e32 v28, 0, v28
	v_fmac_f32_e32 v18, v165, v27
	v_max_f32_e32 v29, 0, v29
	v_fmac_f32_e32 v18, v164, v28
	v_max_f32_e32 v30, 0, v30
	v_fmac_f32_e32 v18, v163, v29
	v_fmac_f32_e32 v18, v162, v30
	v_max_f32_e32 v19, 0, v31
	v_fmac_f32_e32 v18, v161, v19
	v_max_f32_e32 v19, 0, v32
	v_fmac_f32_e32 v18, v160, v19
	v_max_f32_e32 v19, 0, v33
	v_fmac_f32_e32 v18, v89, v19
	v_not_b32_e32 v19, v18
	v_or_b32_e32 v20, 0x80000000, v18
	v_cmp_gt_i32_e32 vcc, 0, v18
	s_nop 1
	v_cndmask_b32_e32 v18, v20, v19, vcc
	v_cmp_le_u32_e32 vcc, v116, v87
	s_nop 1
	v_cndmask_b32_e32 v197, 0, v18, vcc

.LBB0_488:
	s_or_b64 exec, exec, s[84:85]
	v_mfma_f32_32x32x16_bf16 v[18:33], v[38:41], v[58:61], 0
	v_mfma_f32_32x32x16_bf16 v[18:33], v[46:49], v[54:57], v[18:33]
	v_mfma_f32_32x32x16_bf16 v[18:33], v[34:37], v[50:53], v[18:33]
	v_mfma_f32_32x32x16_bf16 v[18:33], v[42:45], v[62:65], v[18:33]
	s_waitcnt vmcnt(12)
	ds_read_b128 v[58:61], v74 offset:12288
	ds_read_b128 v[54:57], v75 offset:12288
	ds_read_b128 v[50:53], v76 offset:12288
	ds_read_b128 v[62:65], v77 offset:12288
	s_nop 8
	v_max_f32_e32 v18, 0, v18
	v_max_f32_e32 v19, 0, v19
	v_fma_f32 v18, v174, v18, 0
	v_max_f32_e32 v20, 0, v20
	v_fmac_f32_e32 v18, v173, v19
	v_max_f32_e32 v21, 0, v21
	v_fmac_f32_e32 v18, v172, v20
	v_max_f32_e32 v22, 0, v22
	v_fmac_f32_e32 v18, v171, v21
	v_max_f32_e32 v23, 0, v23
	v_fmac_f32_e32 v18, v170, v22
	v_max_f32_e32 v24, 0, v24
	v_fmac_f32_e32 v18, v169, v23
	v_max_f32_e32 v25, 0, v25
	v_fmac_f32_e32 v18, v168, v24
	v_max_f32_e32 v26, 0, v26
	v_fmac_f32_e32 v18, v167, v25
	v_max_f32_e32 v27, 0, v27
	v_fmac_f32_e32 v18, v166, v26
	v_max_f32_e32 v28, 0, v28
	v_fmac_f32_e32 v18, v165, v27
	v_max_f32_e32 v29, 0, v29
	v_fmac_f32_e32 v18, v164, v28
	v_max_f32_e32 v30, 0, v30
	v_fmac_f32_e32 v18, v163, v29
	v_fmac_f32_e32 v18, v162, v30
	v_max_f32_e32 v19, 0, v31
	v_fmac_f32_e32 v18, v161, v19
	v_max_f32_e32 v19, 0, v32
	v_fmac_f32_e32 v18, v160, v19
	v_max_f32_e32 v19, 0, v33
	v_fmac_f32_e32 v18, v89, v19
	v_not_b32_e32 v19, v18
	v_or_b32_e32 v20, 0x80000000, v18
	v_cmp_gt_i32_e32 vcc, 0, v18
	s_nop 1
	v_cndmask_b32_e32 v18, v20, v19, vcc
	v_cmp_le_u32_e32 vcc, v117, v87
	s_nop 1
	v_cndmask_b32_e32 v216, 0, v18, vcc

.LBB0_492:
	s_or_b64 exec, exec, s[84:85]
	v_mfma_f32_32x32x16_bf16 v[18:33], v[38:41], v[58:61], 0
	v_mfma_f32_32x32x16_bf16 v[18:33], v[46:49], v[54:57], v[18:33]
	v_mfma_f32_32x32x16_bf16 v[18:33], v[34:37], v[50:53], v[18:33]
	v_mfma_f32_32x32x16_bf16 v[18:33], v[42:45], v[62:65], v[18:33]
	s_waitcnt vmcnt(12)
	ds_read_b128 v[58:61], v74 offset:0
	ds_read_b128 v[54:57], v75 offset:0
	ds_read_b128 v[50:53], v76 offset:0
	ds_read_b128 v[62:65], v77 offset:0
	s_nop 8
	v_max_f32_e32 v18, 0, v18
	v_max_f32_e32 v19, 0, v19
	v_fma_f32 v18, v174, v18, 0
	v_max_f32_e32 v20, 0, v20
	v_fmac_f32_e32 v18, v173, v19
	v_max_f32_e32 v21, 0, v21
	v_fmac_f32_e32 v18, v172, v20
	v_max_f32_e32 v22, 0, v22
	v_fmac_f32_e32 v18, v171, v21
	v_max_f32_e32 v23, 0, v23
	v_fmac_f32_e32 v18, v170, v22
	v_max_f32_e32 v24, 0, v24
	v_fmac_f32_e32 v18, v169, v23
	v_max_f32_e32 v25, 0, v25
	v_fmac_f32_e32 v18, v168, v24
	v_max_f32_e32 v26, 0, v26
	v_fmac_f32_e32 v18, v167, v25
	v_max_f32_e32 v27, 0, v27
	v_fmac_f32_e32 v18, v166, v26
	v_max_f32_e32 v28, 0, v28
	v_fmac_f32_e32 v18, v165, v27
	v_max_f32_e32 v29, 0, v29
	v_fmac_f32_e32 v18, v164, v28
	v_max_f32_e32 v30, 0, v30
	v_fmac_f32_e32 v18, v163, v29
	v_fmac_f32_e32 v18, v162, v30
	v_max_f32_e32 v19, 0, v31
	v_fmac_f32_e32 v18, v161, v19
	v_max_f32_e32 v19, 0, v32
	v_fmac_f32_e32 v18, v160, v19
	v_max_f32_e32 v19, 0, v33
	v_fmac_f32_e32 v18, v89, v19
	v_not_b32_e32 v19, v18
	v_or_b32_e32 v20, 0x80000000, v18
	v_cmp_gt_i32_e32 vcc, 0, v18
	s_nop 1
	v_cndmask_b32_e32 v18, v20, v19, vcc
	v_cmp_le_u32_e32 vcc, v118, v87
	s_nop 1
	v_cndmask_b32_e32 v217, 0, v18, vcc

.LBB0_496:
	s_or_b64 exec, exec, s[84:85]
	v_mfma_f32_32x32x16_bf16 v[18:33], v[38:41], v[58:61], 0
	v_mfma_f32_32x32x16_bf16 v[18:33], v[46:49], v[54:57], v[18:33]
	v_mfma_f32_32x32x16_bf16 v[18:33], v[34:37], v[50:53], v[18:33]
	v_mfma_f32_32x32x16_bf16 v[18:33], v[42:45], v[62:65], v[18:33]
	s_waitcnt vmcnt(12)
	ds_read_b128 v[58:61], v74 offset:4096
	ds_read_b128 v[54:57], v75 offset:4096
	ds_read_b128 v[50:53], v76 offset:4096
	ds_read_b128 v[62:65], v77 offset:4096
	s_nop 8
	v_max_f32_e32 v18, 0, v18
	v_max_f32_e32 v19, 0, v19
	v_fma_f32 v18, v174, v18, 0
	v_max_f32_e32 v20, 0, v20
	v_fmac_f32_e32 v18, v173, v19
	v_max_f32_e32 v21, 0, v21
	v_fmac_f32_e32 v18, v172, v20
	v_max_f32_e32 v22, 0, v22
	v_fmac_f32_e32 v18, v171, v21
	v_max_f32_e32 v23, 0, v23
	v_fmac_f32_e32 v18, v170, v22
	v_max_f32_e32 v24, 0, v24
	v_fmac_f32_e32 v18, v169, v23
	v_max_f32_e32 v25, 0, v25
	v_fmac_f32_e32 v18, v168, v24
	v_max_f32_e32 v26, 0, v26
	v_fmac_f32_e32 v18, v167, v25
	v_max_f32_e32 v27, 0, v27
	v_fmac_f32_e32 v18, v166, v26
	v_max_f32_e32 v28, 0, v28
	v_fmac_f32_e32 v18, v165, v27
	v_max_f32_e32 v29, 0, v29
	v_fmac_f32_e32 v18, v164, v28
	v_max_f32_e32 v30, 0, v30
	v_fmac_f32_e32 v18, v163, v29
	v_fmac_f32_e32 v18, v162, v30
	v_max_f32_e32 v19, 0, v31
	v_fmac_f32_e32 v18, v161, v19
	v_max_f32_e32 v19, 0, v32
	v_fmac_f32_e32 v18, v160, v19
	v_max_f32_e32 v19, 0, v33
	v_fmac_f32_e32 v18, v89, v19
	v_not_b32_e32 v19, v18
	v_or_b32_e32 v20, 0x80000000, v18
	v_cmp_gt_i32_e32 vcc, 0, v18
	s_nop 1
	v_cndmask_b32_e32 v18, v20, v19, vcc
	v_cmp_le_u32_e32 vcc, v119, v87
	s_nop 1
	v_cndmask_b32_e32 v218, 0, v18, vcc

.LBB0_500:
	s_or_b64 exec, exec, s[84:85]
	v_mfma_f32_32x32x16_bf16 v[18:33], v[38:41], v[58:61], 0
	v_mfma_f32_32x32x16_bf16 v[18:33], v[46:49], v[54:57], v[18:33]
	v_mfma_f32_32x32x16_bf16 v[18:33], v[34:37], v[50:53], v[18:33]
	v_mfma_f32_32x32x16_bf16 v[18:33], v[42:45], v[62:65], v[18:33]
	s_waitcnt vmcnt(12)
	ds_read_b128 v[58:61], v74 offset:8192
	ds_read_b128 v[54:57], v75 offset:8192
	ds_read_b128 v[50:53], v76 offset:8192
	ds_read_b128 v[62:65], v77 offset:8192
	s_nop 8
	v_max_f32_e32 v18, 0, v18
	v_max_f32_e32 v19, 0, v19
	v_fma_f32 v18, v174, v18, 0
	v_max_f32_e32 v20, 0, v20
	v_fmac_f32_e32 v18, v173, v19
	v_max_f32_e32 v21, 0, v21
	v_fmac_f32_e32 v18, v172, v20
	v_max_f32_e32 v22, 0, v22
	v_fmac_f32_e32 v18, v171, v21
	v_max_f32_e32 v23, 0, v23
	v_fmac_f32_e32 v18, v170, v22
	v_max_f32_e32 v24, 0, v24
	v_fmac_f32_e32 v18, v169, v23
	v_max_f32_e32 v25, 0, v25
	v_fmac_f32_e32 v18, v168, v24
	v_max_f32_e32 v26, 0, v26
	v_fmac_f32_e32 v18, v167, v25
	v_max_f32_e32 v27, 0, v27
	v_fmac_f32_e32 v18, v166, v26
	v_max_f32_e32 v28, 0, v28
	v_fmac_f32_e32 v18, v165, v27
	v_max_f32_e32 v29, 0, v29
	v_fmac_f32_e32 v18, v164, v28
	v_max_f32_e32 v30, 0, v30
	v_fmac_f32_e32 v18, v163, v29
	v_fmac_f32_e32 v18, v162, v30
	v_max_f32_e32 v19, 0, v31
	v_fmac_f32_e32 v18, v161, v19
	v_max_f32_e32 v19, 0, v32
	v_fmac_f32_e32 v18, v160, v19
	v_max_f32_e32 v19, 0, v33
	v_fmac_f32_e32 v18, v89, v19
	v_not_b32_e32 v19, v18
	v_or_b32_e32 v20, 0x80000000, v18
	v_cmp_gt_i32_e32 vcc, 0, v18
	s_nop 1
	v_cndmask_b32_e32 v18, v20, v19, vcc
	v_cmp_le_u32_e32 vcc, v120, v87
	s_nop 1
	v_cndmask_b32_e32 v219, 0, v18, vcc

.LBB0_504:
	s_or_b64 exec, exec, s[84:85]
	v_mfma_f32_32x32x16_bf16 v[18:33], v[38:41], v[58:61], 0
	v_mfma_f32_32x32x16_bf16 v[18:33], v[46:49], v[54:57], v[18:33]
	v_mfma_f32_32x32x16_bf16 v[18:33], v[34:37], v[50:53], v[18:33]
	v_mfma_f32_32x32x16_bf16 v[18:33], v[42:45], v[62:65], v[18:33]
	s_waitcnt vmcnt(12)
	ds_read_b128 v[58:61], v74 offset:12288
	ds_read_b128 v[54:57], v75 offset:12288
	ds_read_b128 v[50:53], v76 offset:12288
	ds_read_b128 v[62:65], v77 offset:12288
	s_nop 8
	v_max_f32_e32 v18, 0, v18
	v_max_f32_e32 v19, 0, v19
	v_fma_f32 v18, v174, v18, 0
	v_max_f32_e32 v20, 0, v20
	v_fmac_f32_e32 v18, v173, v19
	v_max_f32_e32 v21, 0, v21
	v_fmac_f32_e32 v18, v172, v20
	v_max_f32_e32 v22, 0, v22
	v_fmac_f32_e32 v18, v171, v21
	v_max_f32_e32 v23, 0, v23
	v_fmac_f32_e32 v18, v170, v22
	v_max_f32_e32 v24, 0, v24
	v_fmac_f32_e32 v18, v169, v23
	v_max_f32_e32 v25, 0, v25
	v_fmac_f32_e32 v18, v168, v24
	v_max_f32_e32 v26, 0, v26
	v_fmac_f32_e32 v18, v167, v25
	v_max_f32_e32 v27, 0, v27
	v_fmac_f32_e32 v18, v166, v26
	v_max_f32_e32 v28, 0, v28
	v_fmac_f32_e32 v18, v165, v27
	v_max_f32_e32 v29, 0, v29
	v_fmac_f32_e32 v18, v164, v28
	v_max_f32_e32 v30, 0, v30
	v_fmac_f32_e32 v18, v163, v29
	v_fmac_f32_e32 v18, v162, v30
	v_max_f32_e32 v19, 0, v31
	v_fmac_f32_e32 v18, v161, v19
	v_max_f32_e32 v19, 0, v32
	v_fmac_f32_e32 v18, v160, v19
	v_max_f32_e32 v19, 0, v33
	v_fmac_f32_e32 v18, v89, v19
	v_not_b32_e32 v19, v18
	v_or_b32_e32 v20, 0x80000000, v18
	v_cmp_gt_i32_e32 vcc, 0, v18
	s_nop 1
	v_cndmask_b32_e32 v18, v20, v19, vcc
	v_cmp_le_u32_e32 vcc, v121, v87
	s_nop 1
	v_cndmask_b32_e32 v220, 0, v18, vcc

.LBB0_508:
	s_or_b64 exec, exec, s[84:85]
	v_mfma_f32_32x32x16_bf16 v[18:33], v[38:41], v[58:61], 0
	v_mfma_f32_32x32x16_bf16 v[18:33], v[46:49], v[54:57], v[18:33]
	v_mfma_f32_32x32x16_bf16 v[18:33], v[34:37], v[50:53], v[18:33]
	v_mfma_f32_32x32x16_bf16 v[18:33], v[42:45], v[62:65], v[18:33]
	s_waitcnt vmcnt(12)
	ds_read_b128 v[58:61], v74 offset:0
	ds_read_b128 v[54:57], v75 offset:0
	ds_read_b128 v[50:53], v76 offset:0
	ds_read_b128 v[62:65], v77 offset:0
	s_nop 8
	v_max_f32_e32 v18, 0, v18
	v_max_f32_e32 v19, 0, v19
	v_fma_f32 v18, v174, v18, 0
	v_max_f32_e32 v20, 0, v20
	v_fmac_f32_e32 v18, v173, v19
	v_max_f32_e32 v21, 0, v21
	v_fmac_f32_e32 v18, v172, v20
	v_max_f32_e32 v22, 0, v22
	v_fmac_f32_e32 v18, v171, v21
	v_max_f32_e32 v23, 0, v23
	v_fmac_f32_e32 v18, v170, v22
	v_max_f32_e32 v24, 0, v24
	v_fmac_f32_e32 v18, v169, v23
	v_max_f32_e32 v25, 0, v25
	v_fmac_f32_e32 v18, v168, v24
	v_max_f32_e32 v26, 0, v26
	v_fmac_f32_e32 v18, v167, v25
	v_max_f32_e32 v27, 0, v27
	v_fmac_f32_e32 v18, v166, v26
	v_max_f32_e32 v28, 0, v28
	v_fmac_f32_e32 v18, v165, v27
	v_max_f32_e32 v29, 0, v29
	v_fmac_f32_e32 v18, v164, v28
	v_max_f32_e32 v30, 0, v30
	v_fmac_f32_e32 v18, v163, v29
	v_fmac_f32_e32 v18, v162, v30
	v_max_f32_e32 v19, 0, v31
	v_fmac_f32_e32 v18, v161, v19
	v_max_f32_e32 v19, 0, v32
	v_fmac_f32_e32 v18, v160, v19
	v_max_f32_e32 v19, 0, v33
	v_fmac_f32_e32 v18, v89, v19
	v_not_b32_e32 v19, v18
	v_or_b32_e32 v20, 0x80000000, v18
	v_cmp_gt_i32_e32 vcc, 0, v18
	s_nop 1
	v_cndmask_b32_e32 v18, v20, v19, vcc
	v_cmp_le_u32_e32 vcc, v122, v87
	s_nop 1
	v_cndmask_b32_e32 v221, 0, v18, vcc

.LBB0_512:
	s_or_b64 exec, exec, s[84:85]
	v_mfma_f32_32x32x16_bf16 v[18:33], v[38:41], v[58:61], 0
	v_mfma_f32_32x32x16_bf16 v[18:33], v[46:49], v[54:57], v[18:33]
	v_mfma_f32_32x32x16_bf16 v[18:33], v[34:37], v[50:53], v[18:33]
	v_mfma_f32_32x32x16_bf16 v[18:33], v[42:45], v[62:65], v[18:33]
	s_waitcnt vmcnt(12)
	ds_read_b128 v[58:61], v74 offset:4096
	ds_read_b128 v[54:57], v75 offset:4096
	ds_read_b128 v[50:53], v76 offset:4096
	ds_read_b128 v[62:65], v77 offset:4096
	s_nop 8
	v_max_f32_e32 v18, 0, v18
	v_max_f32_e32 v19, 0, v19
	v_fma_f32 v18, v174, v18, 0
	v_max_f32_e32 v20, 0, v20
	v_fmac_f32_e32 v18, v173, v19
	v_max_f32_e32 v21, 0, v21
	v_fmac_f32_e32 v18, v172, v20
	v_max_f32_e32 v22, 0, v22
	v_fmac_f32_e32 v18, v171, v21
	v_max_f32_e32 v23, 0, v23
	v_fmac_f32_e32 v18, v170, v22
	v_max_f32_e32 v24, 0, v24
	v_fmac_f32_e32 v18, v169, v23
	v_max_f32_e32 v25, 0, v25
	v_fmac_f32_e32 v18, v168, v24
	v_max_f32_e32 v26, 0, v26
	v_fmac_f32_e32 v18, v167, v25
	v_max_f32_e32 v27, 0, v27
	v_fmac_f32_e32 v18, v166, v26
	v_max_f32_e32 v28, 0, v28
	v_fmac_f32_e32 v18, v165, v27
	v_max_f32_e32 v29, 0, v29
	v_fmac_f32_e32 v18, v164, v28
	v_max_f32_e32 v30, 0, v30
	v_fmac_f32_e32 v18, v163, v29
	v_fmac_f32_e32 v18, v162, v30
	v_max_f32_e32 v19, 0, v31
	v_fmac_f32_e32 v18, v161, v19
	v_max_f32_e32 v19, 0, v32
	v_fmac_f32_e32 v18, v160, v19
	v_max_f32_e32 v19, 0, v33
	v_fmac_f32_e32 v18, v89, v19
	v_not_b32_e32 v19, v18
	v_or_b32_e32 v20, 0x80000000, v18
	v_cmp_gt_i32_e32 vcc, 0, v18
	s_nop 1
	v_cndmask_b32_e32 v18, v20, v19, vcc
	v_cmp_le_u32_e32 vcc, v123, v87
	s_nop 1
	v_cndmask_b32_e32 v222, 0, v18, vcc

.LBB0_516:
	s_or_b64 exec, exec, s[84:85]
	v_mfma_f32_32x32x16_bf16 v[18:33], v[38:41], v[58:61], 0
	v_mfma_f32_32x32x16_bf16 v[18:33], v[46:49], v[54:57], v[18:33]
	v_mfma_f32_32x32x16_bf16 v[18:33], v[34:37], v[50:53], v[18:33]
	v_mfma_f32_32x32x16_bf16 v[18:33], v[42:45], v[62:65], v[18:33]
	s_waitcnt vmcnt(12)
	ds_read_b128 v[58:61], v74 offset:8192
	ds_read_b128 v[54:57], v75 offset:8192
	ds_read_b128 v[50:53], v76 offset:8192
	ds_read_b128 v[62:65], v77 offset:8192
	s_nop 8
	v_max_f32_e32 v18, 0, v18
	v_max_f32_e32 v19, 0, v19
	v_fma_f32 v18, v174, v18, 0
	v_max_f32_e32 v20, 0, v20
	v_fmac_f32_e32 v18, v173, v19
	v_max_f32_e32 v21, 0, v21
	v_fmac_f32_e32 v18, v172, v20
	v_max_f32_e32 v22, 0, v22
	v_fmac_f32_e32 v18, v171, v21
	v_max_f32_e32 v23, 0, v23
	v_fmac_f32_e32 v18, v170, v22
	v_max_f32_e32 v24, 0, v24
	v_fmac_f32_e32 v18, v169, v23
	v_max_f32_e32 v25, 0, v25
	v_fmac_f32_e32 v18, v168, v24
	v_max_f32_e32 v26, 0, v26
	v_fmac_f32_e32 v18, v167, v25
	v_max_f32_e32 v27, 0, v27
	v_fmac_f32_e32 v18, v166, v26
	v_max_f32_e32 v28, 0, v28
	v_fmac_f32_e32 v18, v165, v27
	v_max_f32_e32 v29, 0, v29
	v_fmac_f32_e32 v18, v164, v28
	v_max_f32_e32 v30, 0, v30
	v_fmac_f32_e32 v18, v163, v29
	v_fmac_f32_e32 v18, v162, v30
	v_max_f32_e32 v19, 0, v31
	v_fmac_f32_e32 v18, v161, v19
	v_max_f32_e32 v19, 0, v32
	v_fmac_f32_e32 v18, v160, v19
	v_max_f32_e32 v19, 0, v33
	v_fmac_f32_e32 v18, v89, v19
	v_not_b32_e32 v19, v18
	v_or_b32_e32 v20, 0x80000000, v18
	v_cmp_gt_i32_e32 vcc, 0, v18
	s_nop 1
	v_cndmask_b32_e32 v18, v20, v19, vcc
	v_cmp_le_u32_e32 vcc, v124, v87
	s_nop 1
	v_cndmask_b32_e32 v223, 0, v18, vcc

.LBB0_520:
	s_or_b64 exec, exec, s[84:85]
	v_mfma_f32_32x32x16_bf16 v[18:33], v[38:41], v[58:61], 0
	v_mfma_f32_32x32x16_bf16 v[18:33], v[46:49], v[54:57], v[18:33]
	v_mfma_f32_32x32x16_bf16 v[18:33], v[34:37], v[50:53], v[18:33]
	v_mfma_f32_32x32x16_bf16 v[18:33], v[42:45], v[62:65], v[18:33]
	s_waitcnt vmcnt(12)
	ds_read_b128 v[58:61], v74 offset:12288
	ds_read_b128 v[54:57], v75 offset:12288
	ds_read_b128 v[50:53], v76 offset:12288
	ds_read_b128 v[62:65], v77 offset:12288
	s_nop 8
	v_max_f32_e32 v18, 0, v18
	v_max_f32_e32 v19, 0, v19
	v_fma_f32 v18, v174, v18, 0
	v_max_f32_e32 v20, 0, v20
	v_fmac_f32_e32 v18, v173, v19
	v_max_f32_e32 v21, 0, v21
	v_fmac_f32_e32 v18, v172, v20
	v_max_f32_e32 v22, 0, v22
	v_fmac_f32_e32 v18, v171, v21
	v_max_f32_e32 v23, 0, v23
	v_fmac_f32_e32 v18, v170, v22
	v_max_f32_e32 v24, 0, v24
	v_fmac_f32_e32 v18, v169, v23
	v_max_f32_e32 v25, 0, v25
	v_fmac_f32_e32 v18, v168, v24
	v_max_f32_e32 v26, 0, v26
	v_fmac_f32_e32 v18, v167, v25
	v_max_f32_e32 v27, 0, v27
	v_fmac_f32_e32 v18, v166, v26
	v_max_f32_e32 v28, 0, v28
	v_fmac_f32_e32 v18, v165, v27
	v_max_f32_e32 v29, 0, v29
	v_fmac_f32_e32 v18, v164, v28
	v_max_f32_e32 v30, 0, v30
	v_fmac_f32_e32 v18, v163, v29
	v_fmac_f32_e32 v18, v162, v30
	v_max_f32_e32 v19, 0, v31
	v_fmac_f32_e32 v18, v161, v19
	v_max_f32_e32 v19, 0, v32
	v_fmac_f32_e32 v18, v160, v19
	v_max_f32_e32 v19, 0, v33
	v_fmac_f32_e32 v18, v89, v19
	v_not_b32_e32 v19, v18
	v_or_b32_e32 v20, 0x80000000, v18
	v_cmp_gt_i32_e32 vcc, 0, v18
	s_nop 1
	v_cndmask_b32_e32 v18, v20, v19, vcc
	v_cmp_le_u32_e32 vcc, v125, v87
	s_nop 1
	v_cndmask_b32_e32 v224, 0, v18, vcc

.LBB0_524:
	s_or_b64 exec, exec, s[84:85]
	v_mfma_f32_32x32x16_bf16 v[18:33], v[38:41], v[58:61], 0
	v_mfma_f32_32x32x16_bf16 v[18:33], v[46:49], v[54:57], v[18:33]
	v_mfma_f32_32x32x16_bf16 v[18:33], v[34:37], v[50:53], v[18:33]
	v_mfma_f32_32x32x16_bf16 v[18:33], v[42:45], v[62:65], v[18:33]
	s_waitcnt vmcnt(12)
	ds_read_b128 v[58:61], v74 offset:0
	ds_read_b128 v[54:57], v75 offset:0
	ds_read_b128 v[50:53], v76 offset:0
	ds_read_b128 v[62:65], v77 offset:0
	s_nop 8
	v_max_f32_e32 v18, 0, v18
	v_max_f32_e32 v19, 0, v19
	v_fma_f32 v18, v174, v18, 0
	v_max_f32_e32 v20, 0, v20
	v_fmac_f32_e32 v18, v173, v19
	v_max_f32_e32 v21, 0, v21
	v_fmac_f32_e32 v18, v172, v20
	v_max_f32_e32 v22, 0, v22
	v_fmac_f32_e32 v18, v171, v21
	v_max_f32_e32 v23, 0, v23
	v_fmac_f32_e32 v18, v170, v22
	v_max_f32_e32 v24, 0, v24
	v_fmac_f32_e32 v18, v169, v23
	v_max_f32_e32 v25, 0, v25
	v_fmac_f32_e32 v18, v168, v24
	v_max_f32_e32 v26, 0, v26
	v_fmac_f32_e32 v18, v167, v25
	v_max_f32_e32 v27, 0, v27
	v_fmac_f32_e32 v18, v166, v26
	v_max_f32_e32 v28, 0, v28
	v_fmac_f32_e32 v18, v165, v27
	v_max_f32_e32 v29, 0, v29
	v_fmac_f32_e32 v18, v164, v28
	v_max_f32_e32 v30, 0, v30
	v_fmac_f32_e32 v18, v163, v29
	v_fmac_f32_e32 v18, v162, v30
	v_max_f32_e32 v19, 0, v31
	v_fmac_f32_e32 v18, v161, v19
	v_max_f32_e32 v19, 0, v32
	v_fmac_f32_e32 v18, v160, v19
	v_max_f32_e32 v19, 0, v33
	v_fmac_f32_e32 v18, v89, v19
	v_not_b32_e32 v19, v18
	v_or_b32_e32 v20, 0x80000000, v18
	v_cmp_gt_i32_e32 vcc, 0, v18
	s_nop 1
	v_cndmask_b32_e32 v18, v20, v19, vcc
	v_cmp_le_u32_e32 vcc, v126, v87
	s_nop 1
	v_cndmask_b32_e32 v225, 0, v18, vcc

.LBB0_528:
	s_or_b64 exec, exec, s[84:85]
	v_mfma_f32_32x32x16_bf16 v[18:33], v[38:41], v[58:61], 0
	v_mfma_f32_32x32x16_bf16 v[18:33], v[46:49], v[54:57], v[18:33]
	v_mfma_f32_32x32x16_bf16 v[18:33], v[34:37], v[50:53], v[18:33]
	v_mfma_f32_32x32x16_bf16 v[18:33], v[42:45], v[62:65], v[18:33]
	s_waitcnt vmcnt(12)
	ds_read_b128 v[58:61], v74 offset:4096
	ds_read_b128 v[54:57], v75 offset:4096
	ds_read_b128 v[50:53], v76 offset:4096
	ds_read_b128 v[62:65], v77 offset:4096
	s_nop 8
	v_max_f32_e32 v18, 0, v18
	v_max_f32_e32 v19, 0, v19
	v_fma_f32 v18, v174, v18, 0
	v_max_f32_e32 v20, 0, v20
	v_fmac_f32_e32 v18, v173, v19
	v_max_f32_e32 v21, 0, v21
	v_fmac_f32_e32 v18, v172, v20
	v_max_f32_e32 v22, 0, v22
	v_fmac_f32_e32 v18, v171, v21
	v_max_f32_e32 v23, 0, v23
	v_fmac_f32_e32 v18, v170, v22
	v_max_f32_e32 v24, 0, v24
	v_fmac_f32_e32 v18, v169, v23
	v_max_f32_e32 v25, 0, v25
	v_fmac_f32_e32 v18, v168, v24
	v_max_f32_e32 v26, 0, v26
	v_fmac_f32_e32 v18, v167, v25
	v_max_f32_e32 v27, 0, v27
	v_fmac_f32_e32 v18, v166, v26
	v_max_f32_e32 v28, 0, v28
	v_fmac_f32_e32 v18, v165, v27
	v_max_f32_e32 v29, 0, v29
	v_fmac_f32_e32 v18, v164, v28
	v_max_f32_e32 v30, 0, v30
	v_fmac_f32_e32 v18, v163, v29
	v_fmac_f32_e32 v18, v162, v30
	v_max_f32_e32 v19, 0, v31
	v_fmac_f32_e32 v18, v161, v19
	v_max_f32_e32 v19, 0, v32
	v_fmac_f32_e32 v18, v160, v19
	v_max_f32_e32 v19, 0, v33
	v_fmac_f32_e32 v18, v89, v19
	v_not_b32_e32 v19, v18
	v_or_b32_e32 v20, 0x80000000, v18
	v_cmp_gt_i32_e32 vcc, 0, v18
	s_nop 1
	v_cndmask_b32_e32 v18, v20, v19, vcc
	v_cmp_le_u32_e32 vcc, v127, v87
	s_nop 1
	v_cndmask_b32_e32 v226, 0, v18, vcc

.LBB0_532:
	s_or_b64 exec, exec, s[84:85]
	v_mfma_f32_32x32x16_bf16 v[18:33], v[38:41], v[58:61], 0
	v_mfma_f32_32x32x16_bf16 v[18:33], v[46:49], v[54:57], v[18:33]
	v_mfma_f32_32x32x16_bf16 v[18:33], v[34:37], v[50:53], v[18:33]
	v_mfma_f32_32x32x16_bf16 v[18:33], v[42:45], v[62:65], v[18:33]
	s_waitcnt vmcnt(12)
	ds_read_b128 v[58:61], v74 offset:8192
	ds_read_b128 v[54:57], v75 offset:8192
	ds_read_b128 v[50:53], v76 offset:8192
	ds_read_b128 v[62:65], v77 offset:8192
	s_nop 8
	v_max_f32_e32 v18, 0, v18
	v_max_f32_e32 v19, 0, v19
	v_fma_f32 v18, v174, v18, 0
	v_max_f32_e32 v20, 0, v20
	v_fmac_f32_e32 v18, v173, v19
	v_max_f32_e32 v21, 0, v21
	v_fmac_f32_e32 v18, v172, v20
	v_max_f32_e32 v22, 0, v22
	v_fmac_f32_e32 v18, v171, v21
	v_max_f32_e32 v23, 0, v23
	v_fmac_f32_e32 v18, v170, v22
	v_max_f32_e32 v24, 0, v24
	v_fmac_f32_e32 v18, v169, v23
	v_max_f32_e32 v25, 0, v25
	v_fmac_f32_e32 v18, v168, v24
	v_max_f32_e32 v26, 0, v26
	v_fmac_f32_e32 v18, v167, v25
	v_max_f32_e32 v27, 0, v27
	v_fmac_f32_e32 v18, v166, v26
	v_max_f32_e32 v28, 0, v28
	v_fmac_f32_e32 v18, v165, v27
	v_max_f32_e32 v29, 0, v29
	v_fmac_f32_e32 v18, v164, v28
	v_max_f32_e32 v30, 0, v30
	v_fmac_f32_e32 v18, v163, v29
	v_fmac_f32_e32 v18, v162, v30
	v_max_f32_e32 v19, 0, v31
	v_fmac_f32_e32 v18, v161, v19
	v_max_f32_e32 v19, 0, v32
	v_fmac_f32_e32 v18, v160, v19
	v_max_f32_e32 v19, 0, v33
	v_fmac_f32_e32 v18, v89, v19
	v_not_b32_e32 v19, v18
	v_or_b32_e32 v20, 0x80000000, v18
	v_cmp_gt_i32_e32 vcc, 0, v18
	s_nop 1
	v_cndmask_b32_e32 v18, v20, v19, vcc
	v_cmp_le_u32_e32 vcc, v128, v87
	s_nop 1
	v_cndmask_b32_e32 v227, 0, v18, vcc

.LBB0_536:
	s_or_b64 exec, exec, s[84:85]
	v_mfma_f32_32x32x16_bf16 v[18:33], v[38:41], v[58:61], 0
	v_mfma_f32_32x32x16_bf16 v[18:33], v[46:49], v[54:57], v[18:33]
	v_mfma_f32_32x32x16_bf16 v[18:33], v[34:37], v[50:53], v[18:33]
	v_mfma_f32_32x32x16_bf16 v[18:33], v[42:45], v[62:65], v[18:33]
	s_waitcnt vmcnt(12)
	ds_read_b128 v[58:61], v74 offset:12288
	ds_read_b128 v[54:57], v75 offset:12288
	ds_read_b128 v[50:53], v76 offset:12288
	ds_read_b128 v[62:65], v77 offset:12288
	s_nop 8
	v_max_f32_e32 v18, 0, v18
	v_max_f32_e32 v19, 0, v19
	v_fma_f32 v18, v174, v18, 0
	v_max_f32_e32 v20, 0, v20
	v_fmac_f32_e32 v18, v173, v19
	v_max_f32_e32 v21, 0, v21
	v_fmac_f32_e32 v18, v172, v20
	v_max_f32_e32 v22, 0, v22
	v_fmac_f32_e32 v18, v171, v21
	v_max_f32_e32 v23, 0, v23
	v_fmac_f32_e32 v18, v170, v22
	v_max_f32_e32 v24, 0, v24
	v_fmac_f32_e32 v18, v169, v23
	v_max_f32_e32 v25, 0, v25
	v_fmac_f32_e32 v18, v168, v24
	v_max_f32_e32 v26, 0, v26
	v_fmac_f32_e32 v18, v167, v25
	v_max_f32_e32 v27, 0, v27
	v_fmac_f32_e32 v18, v166, v26
	v_max_f32_e32 v28, 0, v28
	v_fmac_f32_e32 v18, v165, v27
	v_max_f32_e32 v29, 0, v29
	v_fmac_f32_e32 v18, v164, v28
	v_max_f32_e32 v30, 0, v30
	v_fmac_f32_e32 v18, v163, v29
	v_fmac_f32_e32 v18, v162, v30
	v_max_f32_e32 v19, 0, v31
	v_fmac_f32_e32 v18, v161, v19
	v_max_f32_e32 v19, 0, v32
	v_fmac_f32_e32 v18, v160, v19
	v_max_f32_e32 v19, 0, v33
	v_fmac_f32_e32 v18, v89, v19
	v_not_b32_e32 v19, v18
	v_or_b32_e32 v20, 0x80000000, v18
	v_cmp_gt_i32_e32 vcc, 0, v18
	s_nop 1
	v_cndmask_b32_e32 v18, v20, v19, vcc
	v_cmp_le_u32_e32 vcc, v129, v87
	s_nop 1
	v_cndmask_b32_e32 v228, 0, v18, vcc

.LBB0_540:
	s_or_b64 exec, exec, s[84:85]
	v_mfma_f32_32x32x16_bf16 v[18:33], v[38:41], v[58:61], 0
	v_mfma_f32_32x32x16_bf16 v[18:33], v[46:49], v[54:57], v[18:33]
	v_mfma_f32_32x32x16_bf16 v[18:33], v[34:37], v[50:53], v[18:33]
	v_mfma_f32_32x32x16_bf16 v[18:33], v[42:45], v[62:65], v[18:33]
	s_waitcnt vmcnt(12)
	ds_read_b128 v[58:61], v74 offset:0
	ds_read_b128 v[54:57], v75 offset:0
	ds_read_b128 v[50:53], v76 offset:0
	ds_read_b128 v[62:65], v77 offset:0
	s_nop 8
	v_max_f32_e32 v18, 0, v18
	v_max_f32_e32 v19, 0, v19
	v_fma_f32 v18, v174, v18, 0
	v_max_f32_e32 v20, 0, v20
	v_fmac_f32_e32 v18, v173, v19
	v_max_f32_e32 v21, 0, v21
	v_fmac_f32_e32 v18, v172, v20
	v_max_f32_e32 v22, 0, v22
	v_fmac_f32_e32 v18, v171, v21
	v_max_f32_e32 v23, 0, v23
	v_fmac_f32_e32 v18, v170, v22
	v_max_f32_e32 v24, 0, v24
	v_fmac_f32_e32 v18, v169, v23
	v_max_f32_e32 v25, 0, v25
	v_fmac_f32_e32 v18, v168, v24
	v_max_f32_e32 v26, 0, v26
	v_fmac_f32_e32 v18, v167, v25
	v_max_f32_e32 v27, 0, v27
	v_fmac_f32_e32 v18, v166, v26
	v_max_f32_e32 v28, 0, v28
	v_fmac_f32_e32 v18, v165, v27
	v_max_f32_e32 v29, 0, v29
	v_fmac_f32_e32 v18, v164, v28
	v_max_f32_e32 v30, 0, v30
	v_fmac_f32_e32 v18, v163, v29
	v_fmac_f32_e32 v18, v162, v30
	v_max_f32_e32 v19, 0, v31
	v_fmac_f32_e32 v18, v161, v19
	v_max_f32_e32 v19, 0, v32
	v_fmac_f32_e32 v18, v160, v19
	v_max_f32_e32 v19, 0, v33
	v_fmac_f32_e32 v18, v89, v19
	v_not_b32_e32 v19, v18
	v_or_b32_e32 v20, 0x80000000, v18
	v_cmp_gt_i32_e32 vcc, 0, v18
	s_nop 1
	v_cndmask_b32_e32 v18, v20, v19, vcc
	v_cmp_le_u32_e32 vcc, v130, v87
	s_nop 1
	v_cndmask_b32_e32 v229, 0, v18, vcc

.LBB0_544:
	s_or_b64 exec, exec, s[84:85]
	v_mfma_f32_32x32x16_bf16 v[18:33], v[38:41], v[58:61], 0
	v_mfma_f32_32x32x16_bf16 v[18:33], v[46:49], v[54:57], v[18:33]
	v_mfma_f32_32x32x16_bf16 v[18:33], v[34:37], v[50:53], v[18:33]
	v_mfma_f32_32x32x16_bf16 v[18:33], v[42:45], v[62:65], v[18:33]
	s_waitcnt vmcnt(12)
	ds_read_b128 v[58:61], v74 offset:4096
	ds_read_b128 v[54:57], v75 offset:4096
	ds_read_b128 v[50:53], v76 offset:4096
	ds_read_b128 v[62:65], v77 offset:4096
	s_nop 8
	v_max_f32_e32 v18, 0, v18
	v_max_f32_e32 v19, 0, v19
	v_fma_f32 v18, v174, v18, 0
	v_max_f32_e32 v20, 0, v20
	v_fmac_f32_e32 v18, v173, v19
	v_max_f32_e32 v21, 0, v21
	v_fmac_f32_e32 v18, v172, v20
	v_max_f32_e32 v22, 0, v22
	v_fmac_f32_e32 v18, v171, v21
	v_max_f32_e32 v23, 0, v23
	v_fmac_f32_e32 v18, v170, v22
	v_max_f32_e32 v24, 0, v24
	v_fmac_f32_e32 v18, v169, v23
	v_max_f32_e32 v25, 0, v25
	v_fmac_f32_e32 v18, v168, v24
	v_max_f32_e32 v26, 0, v26
	v_fmac_f32_e32 v18, v167, v25
	v_max_f32_e32 v27, 0, v27
	v_fmac_f32_e32 v18, v166, v26
	v_max_f32_e32 v28, 0, v28
	v_fmac_f32_e32 v18, v165, v27
	v_max_f32_e32 v29, 0, v29
	v_fmac_f32_e32 v18, v164, v28
	v_max_f32_e32 v30, 0, v30
	v_fmac_f32_e32 v18, v163, v29
	v_fmac_f32_e32 v18, v162, v30
	v_max_f32_e32 v19, 0, v31
	v_fmac_f32_e32 v18, v161, v19
	v_max_f32_e32 v19, 0, v32
	v_fmac_f32_e32 v18, v160, v19
	v_max_f32_e32 v19, 0, v33
	v_fmac_f32_e32 v18, v89, v19
	v_not_b32_e32 v19, v18
	v_or_b32_e32 v20, 0x80000000, v18
	v_cmp_gt_i32_e32 vcc, 0, v18
	s_nop 1
	v_cndmask_b32_e32 v18, v20, v19, vcc
	v_cmp_le_u32_e32 vcc, v131, v87
	s_nop 1
	v_cndmask_b32_e32 v230, 0, v18, vcc

.LBB0_548:
	s_or_b64 exec, exec, s[84:85]
	v_mfma_f32_32x32x16_bf16 v[18:33], v[38:41], v[58:61], 0
	v_mfma_f32_32x32x16_bf16 v[18:33], v[46:49], v[54:57], v[18:33]
	v_mfma_f32_32x32x16_bf16 v[18:33], v[34:37], v[50:53], v[18:33]
	v_mfma_f32_32x32x16_bf16 v[18:33], v[42:45], v[62:65], v[18:33]
	s_waitcnt vmcnt(12)
	ds_read_b128 v[58:61], v74 offset:8192
	ds_read_b128 v[54:57], v75 offset:8192
	ds_read_b128 v[50:53], v76 offset:8192
	ds_read_b128 v[62:65], v77 offset:8192
	s_nop 8
	v_max_f32_e32 v18, 0, v18
	v_max_f32_e32 v19, 0, v19
	v_fma_f32 v18, v174, v18, 0
	v_max_f32_e32 v20, 0, v20
	v_fmac_f32_e32 v18, v173, v19
	v_max_f32_e32 v21, 0, v21
	v_fmac_f32_e32 v18, v172, v20
	v_max_f32_e32 v22, 0, v22
	v_fmac_f32_e32 v18, v171, v21
	v_max_f32_e32 v23, 0, v23
	v_fmac_f32_e32 v18, v170, v22
	v_max_f32_e32 v24, 0, v24
	v_fmac_f32_e32 v18, v169, v23
	v_max_f32_e32 v25, 0, v25
	v_fmac_f32_e32 v18, v168, v24
	v_max_f32_e32 v26, 0, v26
	v_fmac_f32_e32 v18, v167, v25
	v_max_f32_e32 v27, 0, v27
	v_fmac_f32_e32 v18, v166, v26
	v_max_f32_e32 v28, 0, v28
	v_fmac_f32_e32 v18, v165, v27
	v_max_f32_e32 v29, 0, v29
	v_fmac_f32_e32 v18, v164, v28
	v_max_f32_e32 v30, 0, v30
	v_fmac_f32_e32 v18, v163, v29
	v_fmac_f32_e32 v18, v162, v30
	v_max_f32_e32 v19, 0, v31
	v_fmac_f32_e32 v18, v161, v19
	v_max_f32_e32 v19, 0, v32
	v_fmac_f32_e32 v18, v160, v19
	v_max_f32_e32 v19, 0, v33
	v_fmac_f32_e32 v18, v89, v19
	v_not_b32_e32 v19, v18
	v_or_b32_e32 v20, 0x80000000, v18
	v_cmp_gt_i32_e32 vcc, 0, v18
	s_nop 1
	v_cndmask_b32_e32 v18, v20, v19, vcc
	v_cmp_le_u32_e32 vcc, v132, v87
	s_nop 1
	v_cndmask_b32_e32 v231, 0, v18, vcc

.LBB0_552:
	s_or_b64 exec, exec, s[84:85]
	v_mfma_f32_32x32x16_bf16 v[18:33], v[38:41], v[58:61], 0
	v_mfma_f32_32x32x16_bf16 v[18:33], v[46:49], v[54:57], v[18:33]
	v_mfma_f32_32x32x16_bf16 v[18:33], v[34:37], v[50:53], v[18:33]
	v_mfma_f32_32x32x16_bf16 v[18:33], v[42:45], v[62:65], v[18:33]
	s_waitcnt vmcnt(12)
	ds_read_b128 v[58:61], v74 offset:12288
	ds_read_b128 v[54:57], v75 offset:12288
	ds_read_b128 v[50:53], v76 offset:12288
	ds_read_b128 v[62:65], v77 offset:12288
	s_nop 8
	v_max_f32_e32 v18, 0, v18
	v_max_f32_e32 v19, 0, v19
	v_fma_f32 v18, v174, v18, 0
	v_max_f32_e32 v20, 0, v20
	v_fmac_f32_e32 v18, v173, v19
	v_max_f32_e32 v21, 0, v21
	v_fmac_f32_e32 v18, v172, v20
	v_max_f32_e32 v22, 0, v22
	v_fmac_f32_e32 v18, v171, v21
	v_max_f32_e32 v23, 0, v23
	v_fmac_f32_e32 v18, v170, v22
	v_max_f32_e32 v24, 0, v24
	v_fmac_f32_e32 v18, v169, v23
	v_max_f32_e32 v25, 0, v25
	v_fmac_f32_e32 v18, v168, v24
	v_max_f32_e32 v26, 0, v26
	v_fmac_f32_e32 v18, v167, v25
	v_max_f32_e32 v27, 0, v27
	v_fmac_f32_e32 v18, v166, v26
	v_max_f32_e32 v28, 0, v28
	v_fmac_f32_e32 v18, v165, v27
	v_max_f32_e32 v29, 0, v29
	v_fmac_f32_e32 v18, v164, v28
	v_max_f32_e32 v30, 0, v30
	v_fmac_f32_e32 v18, v163, v29
	v_fmac_f32_e32 v18, v162, v30
	v_max_f32_e32 v19, 0, v31
	v_fmac_f32_e32 v18, v161, v19
	v_max_f32_e32 v19, 0, v32
	v_fmac_f32_e32 v18, v160, v19
	v_max_f32_e32 v19, 0, v33
	v_fmac_f32_e32 v18, v89, v19
	v_not_b32_e32 v19, v18
	v_or_b32_e32 v20, 0x80000000, v18
	v_cmp_gt_i32_e32 vcc, 0, v18
	s_nop 1
	v_cndmask_b32_e32 v18, v20, v19, vcc
	v_cmp_le_u32_e32 vcc, v133, v87
	s_nop 1
	v_cndmask_b32_e32 v232, 0, v18, vcc

.LBB0_556:
	s_or_b64 exec, exec, s[84:85]
	v_mfma_f32_32x32x16_bf16 v[18:33], v[38:41], v[58:61], 0
	v_mfma_f32_32x32x16_bf16 v[18:33], v[46:49], v[54:57], v[18:33]
	v_mfma_f32_32x32x16_bf16 v[18:33], v[34:37], v[50:53], v[18:33]
	v_mfma_f32_32x32x16_bf16 v[18:33], v[42:45], v[62:65], v[18:33]
	s_waitcnt vmcnt(12)
	ds_read_b128 v[58:61], v74 offset:0
	ds_read_b128 v[54:57], v75 offset:0
	ds_read_b128 v[50:53], v76 offset:0
	ds_read_b128 v[62:65], v77 offset:0
	s_nop 8
	v_max_f32_e32 v18, 0, v18
	v_max_f32_e32 v19, 0, v19
	v_fma_f32 v18, v174, v18, 0
	v_max_f32_e32 v20, 0, v20
	v_fmac_f32_e32 v18, v173, v19
	v_max_f32_e32 v21, 0, v21
	v_fmac_f32_e32 v18, v172, v20
	v_max_f32_e32 v22, 0, v22
	v_fmac_f32_e32 v18, v171, v21
	v_max_f32_e32 v23, 0, v23
	v_fmac_f32_e32 v18, v170, v22
	v_max_f32_e32 v24, 0, v24
	v_fmac_f32_e32 v18, v169, v23
	v_max_f32_e32 v25, 0, v25
	v_fmac_f32_e32 v18, v168, v24
	v_max_f32_e32 v26, 0, v26
	v_fmac_f32_e32 v18, v167, v25
	v_max_f32_e32 v27, 0, v27
	v_fmac_f32_e32 v18, v166, v26
	v_max_f32_e32 v28, 0, v28
	v_fmac_f32_e32 v18, v165, v27
	v_max_f32_e32 v29, 0, v29
	v_fmac_f32_e32 v18, v164, v28
	v_max_f32_e32 v30, 0, v30
	v_fmac_f32_e32 v18, v163, v29
	v_fmac_f32_e32 v18, v162, v30
	v_max_f32_e32 v19, 0, v31
	v_fmac_f32_e32 v18, v161, v19
	v_max_f32_e32 v19, 0, v32
	v_fmac_f32_e32 v18, v160, v19
	v_max_f32_e32 v19, 0, v33
	v_fmac_f32_e32 v18, v89, v19
	v_not_b32_e32 v19, v18
	v_or_b32_e32 v20, 0x80000000, v18
	v_cmp_gt_i32_e32 vcc, 0, v18
	s_nop 1
	v_cndmask_b32_e32 v18, v20, v19, vcc
	v_cmp_le_u32_e32 vcc, v134, v87
	s_nop 1
	v_cndmask_b32_e32 v233, 0, v18, vcc

.LBB0_560:
	s_or_b64 exec, exec, s[84:85]
	v_mfma_f32_32x32x16_bf16 v[18:33], v[38:41], v[58:61], 0
	v_mfma_f32_32x32x16_bf16 v[18:33], v[46:49], v[54:57], v[18:33]
	v_mfma_f32_32x32x16_bf16 v[18:33], v[34:37], v[50:53], v[18:33]
	v_mfma_f32_32x32x16_bf16 v[18:33], v[42:45], v[62:65], v[18:33]
	s_waitcnt vmcnt(12)
	ds_read_b128 v[58:61], v74 offset:4096
	ds_read_b128 v[54:57], v75 offset:4096
	ds_read_b128 v[50:53], v76 offset:4096
	ds_read_b128 v[62:65], v77 offset:4096
	s_nop 8
	v_max_f32_e32 v18, 0, v18
	v_max_f32_e32 v19, 0, v19
	v_fma_f32 v18, v174, v18, 0
	v_max_f32_e32 v20, 0, v20
	v_fmac_f32_e32 v18, v173, v19
	v_max_f32_e32 v21, 0, v21
	v_fmac_f32_e32 v18, v172, v20
	v_max_f32_e32 v22, 0, v22
	v_fmac_f32_e32 v18, v171, v21
	v_max_f32_e32 v23, 0, v23
	v_fmac_f32_e32 v18, v170, v22
	v_max_f32_e32 v24, 0, v24
	v_fmac_f32_e32 v18, v169, v23
	v_max_f32_e32 v25, 0, v25
	v_fmac_f32_e32 v18, v168, v24
	v_max_f32_e32 v26, 0, v26
	v_fmac_f32_e32 v18, v167, v25
	v_max_f32_e32 v27, 0, v27
	v_fmac_f32_e32 v18, v166, v26
	v_max_f32_e32 v28, 0, v28
	v_fmac_f32_e32 v18, v165, v27
	v_max_f32_e32 v29, 0, v29
	v_fmac_f32_e32 v18, v164, v28
	v_max_f32_e32 v30, 0, v30
	v_fmac_f32_e32 v18, v163, v29
	v_fmac_f32_e32 v18, v162, v30
	v_max_f32_e32 v19, 0, v31
	v_fmac_f32_e32 v18, v161, v19
	v_max_f32_e32 v19, 0, v32
	v_fmac_f32_e32 v18, v160, v19
	v_max_f32_e32 v19, 0, v33
	v_fmac_f32_e32 v18, v89, v19
	v_not_b32_e32 v19, v18
	v_or_b32_e32 v20, 0x80000000, v18
	v_cmp_gt_i32_e32 vcc, 0, v18
	s_nop 1
	v_cndmask_b32_e32 v18, v20, v19, vcc
	v_cmp_le_u32_e32 vcc, v135, v87
	s_nop 1
	v_cndmask_b32_e32 v234, 0, v18, vcc

.LBB0_564:
	s_or_b64 exec, exec, s[84:85]
	v_mfma_f32_32x32x16_bf16 v[18:33], v[38:41], v[58:61], 0
	v_mfma_f32_32x32x16_bf16 v[18:33], v[46:49], v[54:57], v[18:33]
	v_mfma_f32_32x32x16_bf16 v[18:33], v[34:37], v[50:53], v[18:33]
	v_mfma_f32_32x32x16_bf16 v[18:33], v[42:45], v[62:65], v[18:33]
	s_waitcnt vmcnt(12)
	ds_read_b128 v[58:61], v74 offset:8192
	ds_read_b128 v[54:57], v75 offset:8192
	ds_read_b128 v[50:53], v76 offset:8192
	ds_read_b128 v[62:65], v77 offset:8192
	s_nop 8
	v_max_f32_e32 v18, 0, v18
	v_max_f32_e32 v19, 0, v19
	v_fma_f32 v18, v174, v18, 0
	v_max_f32_e32 v20, 0, v20
	v_fmac_f32_e32 v18, v173, v19
	v_max_f32_e32 v21, 0, v21
	v_fmac_f32_e32 v18, v172, v20
	v_max_f32_e32 v22, 0, v22
	v_fmac_f32_e32 v18, v171, v21
	v_max_f32_e32 v23, 0, v23
	v_fmac_f32_e32 v18, v170, v22
	v_max_f32_e32 v24, 0, v24
	v_fmac_f32_e32 v18, v169, v23
	v_max_f32_e32 v25, 0, v25
	v_fmac_f32_e32 v18, v168, v24
	v_max_f32_e32 v26, 0, v26
	v_fmac_f32_e32 v18, v167, v25
	v_max_f32_e32 v27, 0, v27
	v_fmac_f32_e32 v18, v166, v26
	v_max_f32_e32 v28, 0, v28
	v_fmac_f32_e32 v18, v165, v27
	v_max_f32_e32 v29, 0, v29
	v_fmac_f32_e32 v18, v164, v28
	v_max_f32_e32 v30, 0, v30
	v_fmac_f32_e32 v18, v163, v29
	v_fmac_f32_e32 v18, v162, v30
	v_max_f32_e32 v19, 0, v31
	v_fmac_f32_e32 v18, v161, v19
	v_max_f32_e32 v19, 0, v32
	v_fmac_f32_e32 v18, v160, v19
	v_max_f32_e32 v19, 0, v33
	v_fmac_f32_e32 v18, v89, v19
	v_not_b32_e32 v19, v18
	v_or_b32_e32 v20, 0x80000000, v18
	v_cmp_gt_i32_e32 vcc, 0, v18
	s_nop 1
	v_cndmask_b32_e32 v18, v20, v19, vcc
	v_cmp_le_u32_e32 vcc, v136, v87
	s_nop 1
	v_cndmask_b32_e32 v235, 0, v18, vcc

.LBB0_568:
	s_or_b64 exec, exec, s[84:85]
	v_mfma_f32_32x32x16_bf16 v[18:33], v[38:41], v[58:61], 0
	v_mfma_f32_32x32x16_bf16 v[18:33], v[46:49], v[54:57], v[18:33]
	v_mfma_f32_32x32x16_bf16 v[18:33], v[34:37], v[50:53], v[18:33]
	v_mfma_f32_32x32x16_bf16 v[18:33], v[42:45], v[62:65], v[18:33]
	s_waitcnt vmcnt(12)
	ds_read_b128 v[58:61], v74 offset:12288
	ds_read_b128 v[54:57], v75 offset:12288
	ds_read_b128 v[50:53], v76 offset:12288
	ds_read_b128 v[62:65], v77 offset:12288
	s_nop 8
	v_max_f32_e32 v18, 0, v18
	v_max_f32_e32 v19, 0, v19
	v_fma_f32 v18, v174, v18, 0
	v_max_f32_e32 v20, 0, v20
	v_fmac_f32_e32 v18, v173, v19
	v_max_f32_e32 v21, 0, v21
	v_fmac_f32_e32 v18, v172, v20
	v_max_f32_e32 v22, 0, v22
	v_fmac_f32_e32 v18, v171, v21
	v_max_f32_e32 v23, 0, v23
	v_fmac_f32_e32 v18, v170, v22
	v_max_f32_e32 v24, 0, v24
	v_fmac_f32_e32 v18, v169, v23
	v_max_f32_e32 v25, 0, v25
	v_fmac_f32_e32 v18, v168, v24
	v_max_f32_e32 v26, 0, v26
	v_fmac_f32_e32 v18, v167, v25
	v_max_f32_e32 v27, 0, v27
	v_fmac_f32_e32 v18, v166, v26
	v_max_f32_e32 v28, 0, v28
	v_fmac_f32_e32 v18, v165, v27
	v_max_f32_e32 v29, 0, v29
	v_fmac_f32_e32 v18, v164, v28
	v_max_f32_e32 v30, 0, v30
	v_fmac_f32_e32 v18, v163, v29
	v_fmac_f32_e32 v18, v162, v30
	v_max_f32_e32 v19, 0, v31
	v_fmac_f32_e32 v18, v161, v19
	v_max_f32_e32 v19, 0, v32
	v_fmac_f32_e32 v18, v160, v19
	v_max_f32_e32 v19, 0, v33
	v_fmac_f32_e32 v18, v89, v19
	v_not_b32_e32 v19, v18
	v_or_b32_e32 v20, 0x80000000, v18
	v_cmp_gt_i32_e32 vcc, 0, v18
	s_nop 1
	v_cndmask_b32_e32 v18, v20, v19, vcc
	v_cmp_le_u32_e32 vcc, v137, v87
	s_nop 1
	v_cndmask_b32_e32 v236, 0, v18, vcc

.LBB0_572:
	s_or_b64 exec, exec, s[84:85]
	v_mfma_f32_32x32x16_bf16 v[18:33], v[38:41], v[58:61], 0
	v_mfma_f32_32x32x16_bf16 v[18:33], v[46:49], v[54:57], v[18:33]
	v_mfma_f32_32x32x16_bf16 v[18:33], v[34:37], v[50:53], v[18:33]
	v_mfma_f32_32x32x16_bf16 v[18:33], v[42:45], v[62:65], v[18:33]
	s_waitcnt vmcnt(12)
	ds_read_b128 v[58:61], v74 offset:0
	ds_read_b128 v[54:57], v75 offset:0
	ds_read_b128 v[50:53], v76 offset:0
	ds_read_b128 v[62:65], v77 offset:0
	s_nop 8
	v_max_f32_e32 v18, 0, v18
	v_max_f32_e32 v19, 0, v19
	v_fma_f32 v18, v174, v18, 0
	v_max_f32_e32 v20, 0, v20
	v_fmac_f32_e32 v18, v173, v19
	v_max_f32_e32 v21, 0, v21
	v_fmac_f32_e32 v18, v172, v20
	v_max_f32_e32 v22, 0, v22
	v_fmac_f32_e32 v18, v171, v21
	v_max_f32_e32 v23, 0, v23
	v_fmac_f32_e32 v18, v170, v22
	v_max_f32_e32 v24, 0, v24
	v_fmac_f32_e32 v18, v169, v23
	v_max_f32_e32 v25, 0, v25
	v_fmac_f32_e32 v18, v168, v24
	v_max_f32_e32 v26, 0, v26
	v_fmac_f32_e32 v18, v167, v25
	v_max_f32_e32 v27, 0, v27
	v_fmac_f32_e32 v18, v166, v26
	v_max_f32_e32 v28, 0, v28
	v_fmac_f32_e32 v18, v165, v27
	v_max_f32_e32 v29, 0, v29
	v_fmac_f32_e32 v18, v164, v28
	v_max_f32_e32 v30, 0, v30
	v_fmac_f32_e32 v18, v163, v29
	v_fmac_f32_e32 v18, v162, v30
	v_max_f32_e32 v19, 0, v31
	v_fmac_f32_e32 v18, v161, v19
	v_max_f32_e32 v19, 0, v32
	v_fmac_f32_e32 v18, v160, v19
	v_max_f32_e32 v19, 0, v33
	v_fmac_f32_e32 v18, v89, v19
	v_not_b32_e32 v19, v18
	v_or_b32_e32 v20, 0x80000000, v18
	v_cmp_gt_i32_e32 vcc, 0, v18
	s_nop 1
	v_cndmask_b32_e32 v18, v20, v19, vcc
	v_cmp_le_u32_e32 vcc, v138, v87
	s_nop 1
	v_cndmask_b32_e32 v237, 0, v18, vcc

.LBB0_576:
	s_or_b64 exec, exec, s[84:85]
	v_mfma_f32_32x32x16_bf16 v[18:33], v[38:41], v[58:61], 0
	v_mfma_f32_32x32x16_bf16 v[18:33], v[46:49], v[54:57], v[18:33]
	v_mfma_f32_32x32x16_bf16 v[18:33], v[34:37], v[50:53], v[18:33]
	v_mfma_f32_32x32x16_bf16 v[18:33], v[42:45], v[62:65], v[18:33]
	s_waitcnt vmcnt(12)
	ds_read_b128 v[58:61], v74 offset:4096
	ds_read_b128 v[54:57], v75 offset:4096
	ds_read_b128 v[50:53], v76 offset:4096
	ds_read_b128 v[62:65], v77 offset:4096
	s_nop 8
	v_max_f32_e32 v18, 0, v18
	v_max_f32_e32 v19, 0, v19
	v_fma_f32 v18, v174, v18, 0
	v_max_f32_e32 v20, 0, v20
	v_fmac_f32_e32 v18, v173, v19
	v_max_f32_e32 v21, 0, v21
	v_fmac_f32_e32 v18, v172, v20
	v_max_f32_e32 v22, 0, v22
	v_fmac_f32_e32 v18, v171, v21
	v_max_f32_e32 v23, 0, v23
	v_fmac_f32_e32 v18, v170, v22
	v_max_f32_e32 v24, 0, v24
	v_fmac_f32_e32 v18, v169, v23
	v_max_f32_e32 v25, 0, v25
	v_fmac_f32_e32 v18, v168, v24
	v_max_f32_e32 v26, 0, v26
	v_fmac_f32_e32 v18, v167, v25
	v_max_f32_e32 v27, 0, v27
	v_fmac_f32_e32 v18, v166, v26
	v_max_f32_e32 v28, 0, v28
	v_fmac_f32_e32 v18, v165, v27
	v_max_f32_e32 v29, 0, v29
	v_fmac_f32_e32 v18, v164, v28
	v_max_f32_e32 v30, 0, v30
	v_fmac_f32_e32 v18, v163, v29
	v_fmac_f32_e32 v18, v162, v30
	v_max_f32_e32 v19, 0, v31
	v_fmac_f32_e32 v18, v161, v19
	v_max_f32_e32 v19, 0, v32
	v_fmac_f32_e32 v18, v160, v19
	v_max_f32_e32 v19, 0, v33
	v_fmac_f32_e32 v18, v89, v19
	v_not_b32_e32 v19, v18
	v_or_b32_e32 v20, 0x80000000, v18
	v_cmp_gt_i32_e32 vcc, 0, v18
	s_nop 1
	v_cndmask_b32_e32 v18, v20, v19, vcc
	v_cmp_le_u32_e32 vcc, v139, v87
	s_nop 1
	v_cndmask_b32_e32 v238, 0, v18, vcc

.LBB0_580:
	s_or_b64 exec, exec, s[84:85]
	v_mfma_f32_32x32x16_bf16 v[18:33], v[38:41], v[58:61], 0
	v_mfma_f32_32x32x16_bf16 v[18:33], v[46:49], v[54:57], v[18:33]
	v_mfma_f32_32x32x16_bf16 v[18:33], v[34:37], v[50:53], v[18:33]
	v_mfma_f32_32x32x16_bf16 v[18:33], v[42:45], v[62:65], v[18:33]
	s_waitcnt vmcnt(12)
	ds_read_b128 v[58:61], v74 offset:8192
	ds_read_b128 v[54:57], v75 offset:8192
	ds_read_b128 v[50:53], v76 offset:8192
	ds_read_b128 v[62:65], v77 offset:8192
	s_nop 8
	v_max_f32_e32 v18, 0, v18
	v_max_f32_e32 v19, 0, v19
	v_fma_f32 v18, v174, v18, 0
	v_max_f32_e32 v20, 0, v20
	v_fmac_f32_e32 v18, v173, v19
	v_max_f32_e32 v21, 0, v21
	v_fmac_f32_e32 v18, v172, v20
	v_max_f32_e32 v22, 0, v22
	v_fmac_f32_e32 v18, v171, v21
	v_max_f32_e32 v23, 0, v23
	v_fmac_f32_e32 v18, v170, v22
	v_max_f32_e32 v24, 0, v24
	v_fmac_f32_e32 v18, v169, v23
	v_max_f32_e32 v25, 0, v25
	v_fmac_f32_e32 v18, v168, v24
	v_max_f32_e32 v26, 0, v26
	v_fmac_f32_e32 v18, v167, v25
	v_max_f32_e32 v27, 0, v27
	v_fmac_f32_e32 v18, v166, v26
	v_max_f32_e32 v28, 0, v28
	v_fmac_f32_e32 v18, v165, v27
	v_max_f32_e32 v29, 0, v29
	v_fmac_f32_e32 v18, v164, v28
	v_max_f32_e32 v30, 0, v30
	v_fmac_f32_e32 v18, v163, v29
	v_fmac_f32_e32 v18, v162, v30
	v_max_f32_e32 v19, 0, v31
	v_fmac_f32_e32 v18, v161, v19
	v_max_f32_e32 v19, 0, v32
	v_fmac_f32_e32 v18, v160, v19
	v_max_f32_e32 v19, 0, v33
	v_fmac_f32_e32 v18, v89, v19
	v_not_b32_e32 v19, v18
	v_or_b32_e32 v20, 0x80000000, v18
	v_cmp_gt_i32_e32 vcc, 0, v18
	s_nop 1
	v_cndmask_b32_e32 v18, v20, v19, vcc
	v_cmp_le_u32_e32 vcc, v140, v87
	s_nop 1
	v_cndmask_b32_e32 v239, 0, v18, vcc

.LBB0_584:
	s_or_b64 exec, exec, s[84:85]
	v_mfma_f32_32x32x16_bf16 v[18:33], v[38:41], v[58:61], 0
	v_mfma_f32_32x32x16_bf16 v[18:33], v[46:49], v[54:57], v[18:33]
	v_mfma_f32_32x32x16_bf16 v[18:33], v[34:37], v[50:53], v[18:33]
	v_mfma_f32_32x32x16_bf16 v[18:33], v[42:45], v[62:65], v[18:33]
	s_waitcnt vmcnt(12)
	ds_read_b128 v[58:61], v74 offset:12288
	ds_read_b128 v[54:57], v75 offset:12288
	ds_read_b128 v[50:53], v76 offset:12288
	ds_read_b128 v[62:65], v77 offset:12288
	s_nop 8
	v_max_f32_e32 v18, 0, v18
	v_max_f32_e32 v19, 0, v19
	v_fma_f32 v18, v174, v18, 0
	v_max_f32_e32 v20, 0, v20
	v_fmac_f32_e32 v18, v173, v19
	v_max_f32_e32 v21, 0, v21
	v_fmac_f32_e32 v18, v172, v20
	v_max_f32_e32 v22, 0, v22
	v_fmac_f32_e32 v18, v171, v21
	v_max_f32_e32 v23, 0, v23
	v_fmac_f32_e32 v18, v170, v22
	v_max_f32_e32 v24, 0, v24
	v_fmac_f32_e32 v18, v169, v23
	v_max_f32_e32 v25, 0, v25
	v_fmac_f32_e32 v18, v168, v24
	v_max_f32_e32 v26, 0, v26
	v_fmac_f32_e32 v18, v167, v25
	v_max_f32_e32 v27, 0, v27
	v_fmac_f32_e32 v18, v166, v26
	v_max_f32_e32 v28, 0, v28
	v_fmac_f32_e32 v18, v165, v27
	v_max_f32_e32 v29, 0, v29
	v_fmac_f32_e32 v18, v164, v28
	v_max_f32_e32 v30, 0, v30
	v_fmac_f32_e32 v18, v163, v29
	v_fmac_f32_e32 v18, v162, v30
	v_max_f32_e32 v19, 0, v31
	v_fmac_f32_e32 v18, v161, v19
	v_max_f32_e32 v19, 0, v32
	v_fmac_f32_e32 v18, v160, v19
	v_max_f32_e32 v19, 0, v33
	v_fmac_f32_e32 v18, v89, v19
	v_not_b32_e32 v19, v18
	v_or_b32_e32 v20, 0x80000000, v18
	v_cmp_gt_i32_e32 vcc, 0, v18
	s_nop 1
	v_cndmask_b32_e32 v18, v20, v19, vcc
	v_cmp_le_u32_e32 vcc, v141, v87
	s_nop 1
	v_cndmask_b32_e32 v240, 0, v18, vcc

.LBB0_588:
	s_or_b64 exec, exec, s[84:85]
	v_mfma_f32_32x32x16_bf16 v[18:33], v[38:41], v[58:61], 0
	v_mfma_f32_32x32x16_bf16 v[18:33], v[46:49], v[54:57], v[18:33]
	v_mfma_f32_32x32x16_bf16 v[18:33], v[34:37], v[50:53], v[18:33]
	v_mfma_f32_32x32x16_bf16 v[18:33], v[42:45], v[62:65], v[18:33]
	s_waitcnt vmcnt(12)
	ds_read_b128 v[58:61], v74 offset:0
	ds_read_b128 v[54:57], v75 offset:0
	ds_read_b128 v[50:53], v76 offset:0
	ds_read_b128 v[62:65], v77 offset:0
	s_nop 8
	v_max_f32_e32 v18, 0, v18
	v_max_f32_e32 v19, 0, v19
	v_fma_f32 v18, v174, v18, 0
	v_max_f32_e32 v20, 0, v20
	v_fmac_f32_e32 v18, v173, v19
	v_max_f32_e32 v21, 0, v21
	v_fmac_f32_e32 v18, v172, v20
	v_max_f32_e32 v22, 0, v22
	v_fmac_f32_e32 v18, v171, v21
	v_max_f32_e32 v23, 0, v23
	v_fmac_f32_e32 v18, v170, v22
	v_max_f32_e32 v24, 0, v24
	v_fmac_f32_e32 v18, v169, v23
	v_max_f32_e32 v25, 0, v25
	v_fmac_f32_e32 v18, v168, v24
	v_max_f32_e32 v26, 0, v26
	v_fmac_f32_e32 v18, v167, v25
	v_max_f32_e32 v27, 0, v27
	v_fmac_f32_e32 v18, v166, v26
	v_max_f32_e32 v28, 0, v28
	v_fmac_f32_e32 v18, v165, v27
	v_max_f32_e32 v29, 0, v29
	v_fmac_f32_e32 v18, v164, v28
	v_max_f32_e32 v30, 0, v30
	v_fmac_f32_e32 v18, v163, v29
	v_fmac_f32_e32 v18, v162, v30
	v_max_f32_e32 v19, 0, v31
	v_fmac_f32_e32 v18, v161, v19
	v_max_f32_e32 v19, 0, v32
	v_fmac_f32_e32 v18, v160, v19
	v_max_f32_e32 v19, 0, v33
	v_fmac_f32_e32 v18, v89, v19
	v_not_b32_e32 v19, v18
	v_or_b32_e32 v20, 0x80000000, v18
	v_cmp_gt_i32_e32 vcc, 0, v18
	s_nop 1
	v_cndmask_b32_e32 v18, v20, v19, vcc
	v_cmp_le_u32_e32 vcc, v142, v87
	s_nop 1
	v_cndmask_b32_e32 v241, 0, v18, vcc

.LBB0_592:
	s_or_b64 exec, exec, s[84:85]
	v_mfma_f32_32x32x16_bf16 v[18:33], v[38:41], v[58:61], 0
	v_mfma_f32_32x32x16_bf16 v[18:33], v[46:49], v[54:57], v[18:33]
	v_mfma_f32_32x32x16_bf16 v[18:33], v[34:37], v[50:53], v[18:33]
	v_mfma_f32_32x32x16_bf16 v[18:33], v[42:45], v[62:65], v[18:33]
	s_waitcnt vmcnt(12)
	ds_read_b128 v[58:61], v74 offset:4096
	ds_read_b128 v[54:57], v75 offset:4096
	ds_read_b128 v[50:53], v76 offset:4096
	ds_read_b128 v[62:65], v77 offset:4096
	s_nop 8
	v_max_f32_e32 v18, 0, v18
	v_max_f32_e32 v19, 0, v19
	v_fma_f32 v18, v174, v18, 0
	v_max_f32_e32 v20, 0, v20
	v_fmac_f32_e32 v18, v173, v19
	v_max_f32_e32 v21, 0, v21
	v_fmac_f32_e32 v18, v172, v20
	v_max_f32_e32 v22, 0, v22
	v_fmac_f32_e32 v18, v171, v21
	v_max_f32_e32 v23, 0, v23
	v_fmac_f32_e32 v18, v170, v22
	v_max_f32_e32 v24, 0, v24
	v_fmac_f32_e32 v18, v169, v23
	v_max_f32_e32 v25, 0, v25
	v_fmac_f32_e32 v18, v168, v24
	v_max_f32_e32 v26, 0, v26
	v_fmac_f32_e32 v18, v167, v25
	v_max_f32_e32 v27, 0, v27
	v_fmac_f32_e32 v18, v166, v26
	v_max_f32_e32 v28, 0, v28
	v_fmac_f32_e32 v18, v165, v27
	v_max_f32_e32 v29, 0, v29
	v_fmac_f32_e32 v18, v164, v28
	v_max_f32_e32 v30, 0, v30
	v_fmac_f32_e32 v18, v163, v29
	v_fmac_f32_e32 v18, v162, v30
	v_max_f32_e32 v19, 0, v31
	v_fmac_f32_e32 v18, v161, v19
	v_max_f32_e32 v19, 0, v32
	v_fmac_f32_e32 v18, v160, v19
	v_max_f32_e32 v19, 0, v33
	v_fmac_f32_e32 v18, v89, v19
	v_not_b32_e32 v19, v18
	v_or_b32_e32 v20, 0x80000000, v18
	v_cmp_gt_i32_e32 vcc, 0, v18
	s_nop 1
	v_cndmask_b32_e32 v18, v20, v19, vcc
	v_cmp_le_u32_e32 vcc, v143, v87
	s_nop 1
	v_cndmask_b32_e32 v242, 0, v18, vcc

.LBB0_596:
	s_or_b64 exec, exec, s[84:85]
	v_mfma_f32_32x32x16_bf16 v[18:33], v[38:41], v[58:61], 0
	v_mfma_f32_32x32x16_bf16 v[18:33], v[46:49], v[54:57], v[18:33]
	v_mfma_f32_32x32x16_bf16 v[18:33], v[34:37], v[50:53], v[18:33]
	v_mfma_f32_32x32x16_bf16 v[18:33], v[42:45], v[62:65], v[18:33]
	s_waitcnt vmcnt(12)
	ds_read_b128 v[58:61], v74 offset:8192
	ds_read_b128 v[54:57], v75 offset:8192
	ds_read_b128 v[50:53], v76 offset:8192
	ds_read_b128 v[62:65], v77 offset:8192
	s_nop 8
	v_max_f32_e32 v18, 0, v18
	v_max_f32_e32 v19, 0, v19
	v_fma_f32 v18, v174, v18, 0
	v_max_f32_e32 v20, 0, v20
	v_fmac_f32_e32 v18, v173, v19
	v_max_f32_e32 v21, 0, v21
	v_fmac_f32_e32 v18, v172, v20
	v_max_f32_e32 v22, 0, v22
	v_fmac_f32_e32 v18, v171, v21
	v_max_f32_e32 v23, 0, v23
	v_fmac_f32_e32 v18, v170, v22
	v_max_f32_e32 v24, 0, v24
	v_fmac_f32_e32 v18, v169, v23
	v_max_f32_e32 v25, 0, v25
	v_fmac_f32_e32 v18, v168, v24
	v_max_f32_e32 v26, 0, v26
	v_fmac_f32_e32 v18, v167, v25
	v_max_f32_e32 v27, 0, v27
	v_fmac_f32_e32 v18, v166, v26
	v_max_f32_e32 v28, 0, v28
	v_fmac_f32_e32 v18, v165, v27
	v_max_f32_e32 v29, 0, v29
	v_fmac_f32_e32 v18, v164, v28
	v_max_f32_e32 v30, 0, v30
	v_fmac_f32_e32 v18, v163, v29
	v_fmac_f32_e32 v18, v162, v30
	v_max_f32_e32 v19, 0, v31
	v_fmac_f32_e32 v18, v161, v19
	v_max_f32_e32 v19, 0, v32
	v_fmac_f32_e32 v18, v160, v19
	v_max_f32_e32 v19, 0, v33
	v_fmac_f32_e32 v18, v89, v19
	v_not_b32_e32 v19, v18
	v_or_b32_e32 v20, 0x80000000, v18
	v_cmp_gt_i32_e32 vcc, 0, v18
	s_nop 1
	v_cndmask_b32_e32 v18, v20, v19, vcc
	v_cmp_le_u32_e32 vcc, v144, v87
	s_nop 1
	v_cndmask_b32_e32 v243, 0, v18, vcc

.LBB0_600:
	s_or_b64 exec, exec, s[84:85]
	v_mfma_f32_32x32x16_bf16 v[18:33], v[38:41], v[58:61], 0
	v_mfma_f32_32x32x16_bf16 v[18:33], v[46:49], v[54:57], v[18:33]
	v_mfma_f32_32x32x16_bf16 v[18:33], v[34:37], v[50:53], v[18:33]
	v_mfma_f32_32x32x16_bf16 v[18:33], v[42:45], v[62:65], v[18:33]
	s_waitcnt vmcnt(12)
	ds_read_b128 v[58:61], v74 offset:12288
	ds_read_b128 v[54:57], v75 offset:12288
	ds_read_b128 v[50:53], v76 offset:12288
	ds_read_b128 v[62:65], v77 offset:12288
	s_nop 8
	v_max_f32_e32 v18, 0, v18
	v_max_f32_e32 v19, 0, v19
	v_fma_f32 v18, v174, v18, 0
	v_max_f32_e32 v20, 0, v20
	v_fmac_f32_e32 v18, v173, v19
	v_max_f32_e32 v21, 0, v21
	v_fmac_f32_e32 v18, v172, v20
	v_max_f32_e32 v22, 0, v22
	v_fmac_f32_e32 v18, v171, v21
	v_max_f32_e32 v23, 0, v23
	v_fmac_f32_e32 v18, v170, v22
	v_max_f32_e32 v24, 0, v24
	v_fmac_f32_e32 v18, v169, v23
	v_max_f32_e32 v25, 0, v25
	v_fmac_f32_e32 v18, v168, v24
	v_max_f32_e32 v26, 0, v26
	v_fmac_f32_e32 v18, v167, v25
	v_max_f32_e32 v27, 0, v27
	v_fmac_f32_e32 v18, v166, v26
	v_max_f32_e32 v28, 0, v28
	v_fmac_f32_e32 v18, v165, v27
	v_max_f32_e32 v29, 0, v29
	v_fmac_f32_e32 v18, v164, v28
	v_max_f32_e32 v30, 0, v30
	v_fmac_f32_e32 v18, v163, v29
	v_fmac_f32_e32 v18, v162, v30
	v_max_f32_e32 v19, 0, v31
	v_fmac_f32_e32 v18, v161, v19
	v_max_f32_e32 v19, 0, v32
	v_fmac_f32_e32 v18, v160, v19
	v_max_f32_e32 v19, 0, v33
	v_fmac_f32_e32 v18, v89, v19
	v_not_b32_e32 v19, v18
	v_or_b32_e32 v20, 0x80000000, v18
	v_cmp_gt_i32_e32 vcc, 0, v18
	s_nop 1
	v_cndmask_b32_e32 v18, v20, v19, vcc
	v_cmp_le_u32_e32 vcc, v145, v87
	s_nop 1
	v_cndmask_b32_e32 v244, 0, v18, vcc

.LBB0_604:
	s_or_b64 exec, exec, s[84:85]
	v_mfma_f32_32x32x16_bf16 v[18:33], v[38:41], v[58:61], 0
	v_mfma_f32_32x32x16_bf16 v[18:33], v[46:49], v[54:57], v[18:33]
	v_mfma_f32_32x32x16_bf16 v[18:33], v[34:37], v[50:53], v[18:33]
	v_mfma_f32_32x32x16_bf16 v[18:33], v[42:45], v[62:65], v[18:33]
	s_waitcnt vmcnt(12)
	ds_read_b128 v[58:61], v74 offset:0
	ds_read_b128 v[54:57], v75 offset:0
	ds_read_b128 v[50:53], v76 offset:0
	ds_read_b128 v[62:65], v77 offset:0
	s_nop 8
	v_max_f32_e32 v18, 0, v18
	v_max_f32_e32 v19, 0, v19
	v_fma_f32 v18, v174, v18, 0
	v_max_f32_e32 v20, 0, v20
	v_fmac_f32_e32 v18, v173, v19
	v_max_f32_e32 v21, 0, v21
	v_fmac_f32_e32 v18, v172, v20
	v_max_f32_e32 v22, 0, v22
	v_fmac_f32_e32 v18, v171, v21
	v_max_f32_e32 v23, 0, v23
	v_fmac_f32_e32 v18, v170, v22
	v_max_f32_e32 v24, 0, v24
	v_fmac_f32_e32 v18, v169, v23
	v_max_f32_e32 v25, 0, v25
	v_fmac_f32_e32 v18, v168, v24
	v_max_f32_e32 v26, 0, v26
	v_fmac_f32_e32 v18, v167, v25
	v_max_f32_e32 v27, 0, v27
	v_fmac_f32_e32 v18, v166, v26
	v_max_f32_e32 v28, 0, v28
	v_fmac_f32_e32 v18, v165, v27
	v_max_f32_e32 v29, 0, v29
	v_fmac_f32_e32 v18, v164, v28
	v_max_f32_e32 v30, 0, v30
	v_fmac_f32_e32 v18, v163, v29
	v_fmac_f32_e32 v18, v162, v30
	v_max_f32_e32 v19, 0, v31
	v_fmac_f32_e32 v18, v161, v19
	v_max_f32_e32 v19, 0, v32
	v_fmac_f32_e32 v18, v160, v19
	v_max_f32_e32 v19, 0, v33
	v_fmac_f32_e32 v18, v89, v19
	v_not_b32_e32 v19, v18
	v_or_b32_e32 v20, 0x80000000, v18
	v_cmp_gt_i32_e32 vcc, 0, v18
	s_nop 1
	v_cndmask_b32_e32 v18, v20, v19, vcc
	v_cmp_le_u32_e32 vcc, v146, v87
	s_nop 1
	v_cndmask_b32_e32 v245, 0, v18, vcc

.LBB0_608:
	s_or_b64 exec, exec, s[84:85]
	v_mfma_f32_32x32x16_bf16 v[18:33], v[38:41], v[58:61], 0
	v_mfma_f32_32x32x16_bf16 v[18:33], v[46:49], v[54:57], v[18:33]
	v_mfma_f32_32x32x16_bf16 v[18:33], v[34:37], v[50:53], v[18:33]
	v_mfma_f32_32x32x16_bf16 v[18:33], v[42:45], v[62:65], v[18:33]
	s_waitcnt vmcnt(12)
	ds_read_b128 v[58:61], v74 offset:4096
	ds_read_b128 v[54:57], v75 offset:4096
	ds_read_b128 v[50:53], v76 offset:4096
	ds_read_b128 v[62:65], v77 offset:4096
	s_nop 8
	v_max_f32_e32 v18, 0, v18
	v_max_f32_e32 v19, 0, v19
	v_fma_f32 v18, v174, v18, 0
	v_max_f32_e32 v20, 0, v20
	v_fmac_f32_e32 v18, v173, v19
	v_max_f32_e32 v21, 0, v21
	v_fmac_f32_e32 v18, v172, v20
	v_max_f32_e32 v22, 0, v22
	v_fmac_f32_e32 v18, v171, v21
	v_max_f32_e32 v23, 0, v23
	v_fmac_f32_e32 v18, v170, v22
	v_max_f32_e32 v24, 0, v24
	v_fmac_f32_e32 v18, v169, v23
	v_max_f32_e32 v25, 0, v25
	v_fmac_f32_e32 v18, v168, v24
	v_max_f32_e32 v26, 0, v26
	v_fmac_f32_e32 v18, v167, v25
	v_max_f32_e32 v27, 0, v27
	v_fmac_f32_e32 v18, v166, v26
	v_max_f32_e32 v28, 0, v28
	v_fmac_f32_e32 v18, v165, v27
	v_max_f32_e32 v29, 0, v29
	v_fmac_f32_e32 v18, v164, v28
	v_max_f32_e32 v30, 0, v30
	v_fmac_f32_e32 v18, v163, v29
	v_fmac_f32_e32 v18, v162, v30
	v_max_f32_e32 v19, 0, v31
	v_fmac_f32_e32 v18, v161, v19
	v_max_f32_e32 v19, 0, v32
	v_fmac_f32_e32 v18, v160, v19
	v_max_f32_e32 v19, 0, v33
	v_fmac_f32_e32 v18, v89, v19
	v_not_b32_e32 v19, v18
	v_or_b32_e32 v20, 0x80000000, v18
	v_cmp_gt_i32_e32 vcc, 0, v18
	s_nop 1
	v_cndmask_b32_e32 v18, v20, v19, vcc
	v_cmp_le_u32_e32 vcc, v147, v87
	s_nop 1
	v_cndmask_b32_e32 v246, 0, v18, vcc

.LBB0_612:
	s_or_b64 exec, exec, s[84:85]
	v_mfma_f32_32x32x16_bf16 v[18:33], v[38:41], v[58:61], 0
	v_mfma_f32_32x32x16_bf16 v[18:33], v[46:49], v[54:57], v[18:33]
	v_mfma_f32_32x32x16_bf16 v[18:33], v[34:37], v[50:53], v[18:33]
	v_mfma_f32_32x32x16_bf16 v[18:33], v[42:45], v[62:65], v[18:33]
	s_waitcnt vmcnt(12)
	ds_read_b128 v[58:61], v74 offset:8192
	ds_read_b128 v[54:57], v75 offset:8192
	ds_read_b128 v[50:53], v76 offset:8192
	ds_read_b128 v[62:65], v77 offset:8192
	s_nop 8
	v_max_f32_e32 v18, 0, v18
	v_max_f32_e32 v19, 0, v19
	v_fma_f32 v18, v174, v18, 0
	v_max_f32_e32 v20, 0, v20
	v_fmac_f32_e32 v18, v173, v19
	v_max_f32_e32 v21, 0, v21
	v_fmac_f32_e32 v18, v172, v20
	v_max_f32_e32 v22, 0, v22
	v_fmac_f32_e32 v18, v171, v21
	v_max_f32_e32 v23, 0, v23
	v_fmac_f32_e32 v18, v170, v22
	v_max_f32_e32 v24, 0, v24
	v_fmac_f32_e32 v18, v169, v23
	v_max_f32_e32 v25, 0, v25
	v_fmac_f32_e32 v18, v168, v24
	v_max_f32_e32 v26, 0, v26
	v_fmac_f32_e32 v18, v167, v25
	v_max_f32_e32 v27, 0, v27
	v_fmac_f32_e32 v18, v166, v26
	v_max_f32_e32 v28, 0, v28
	v_fmac_f32_e32 v18, v165, v27
	v_max_f32_e32 v29, 0, v29
	v_fmac_f32_e32 v18, v164, v28
	v_max_f32_e32 v30, 0, v30
	v_fmac_f32_e32 v18, v163, v29
	v_fmac_f32_e32 v18, v162, v30
	v_max_f32_e32 v19, 0, v31
	v_fmac_f32_e32 v18, v161, v19
	v_max_f32_e32 v19, 0, v32
	v_fmac_f32_e32 v18, v160, v19
	v_max_f32_e32 v19, 0, v33
	v_fmac_f32_e32 v18, v89, v19
	v_not_b32_e32 v19, v18
	v_or_b32_e32 v20, 0x80000000, v18
	v_cmp_gt_i32_e32 vcc, 0, v18
	s_nop 1
	v_cndmask_b32_e32 v18, v20, v19, vcc
	v_cmp_le_u32_e32 vcc, v148, v87
	s_nop 1
	v_cndmask_b32_e32 v247, 0, v18, vcc

.LBB0_616:
	s_or_b64 exec, exec, s[84:85]
	v_mfma_f32_32x32x16_bf16 v[18:33], v[38:41], v[58:61], 0
	v_mfma_f32_32x32x16_bf16 v[18:33], v[46:49], v[54:57], v[18:33]
	v_mfma_f32_32x32x16_bf16 v[18:33], v[34:37], v[50:53], v[18:33]
	v_mfma_f32_32x32x16_bf16 v[18:33], v[42:45], v[62:65], v[18:33]
	s_waitcnt vmcnt(12)
	ds_read_b128 v[58:61], v74 offset:12288
	ds_read_b128 v[54:57], v75 offset:12288
	ds_read_b128 v[50:53], v76 offset:12288
	ds_read_b128 v[62:65], v77 offset:12288
	s_nop 8
	v_max_f32_e32 v18, 0, v18
	v_max_f32_e32 v19, 0, v19
	v_fma_f32 v18, v174, v18, 0
	v_max_f32_e32 v20, 0, v20
	v_fmac_f32_e32 v18, v173, v19
	v_max_f32_e32 v21, 0, v21
	v_fmac_f32_e32 v18, v172, v20
	v_max_f32_e32 v22, 0, v22
	v_fmac_f32_e32 v18, v171, v21
	v_max_f32_e32 v23, 0, v23
	v_fmac_f32_e32 v18, v170, v22
	v_max_f32_e32 v24, 0, v24
	v_fmac_f32_e32 v18, v169, v23
	v_max_f32_e32 v25, 0, v25
	v_fmac_f32_e32 v18, v168, v24
	v_max_f32_e32 v26, 0, v26
	v_fmac_f32_e32 v18, v167, v25
	v_max_f32_e32 v27, 0, v27
	v_fmac_f32_e32 v18, v166, v26
	v_max_f32_e32 v28, 0, v28
	v_fmac_f32_e32 v18, v165, v27
	v_max_f32_e32 v29, 0, v29
	v_fmac_f32_e32 v18, v164, v28
	v_max_f32_e32 v30, 0, v30
	v_fmac_f32_e32 v18, v163, v29
	v_fmac_f32_e32 v18, v162, v30
	v_max_f32_e32 v19, 0, v31
	v_fmac_f32_e32 v18, v161, v19
	v_max_f32_e32 v19, 0, v32
	v_fmac_f32_e32 v18, v160, v19
	v_max_f32_e32 v19, 0, v33
	v_fmac_f32_e32 v18, v89, v19
	v_not_b32_e32 v19, v18
	v_or_b32_e32 v20, 0x80000000, v18
	v_cmp_gt_i32_e32 vcc, 0, v18
	s_nop 1
	v_cndmask_b32_e32 v18, v20, v19, vcc
	v_cmp_le_u32_e32 vcc, v149, v87
	s_nop 1
	v_cndmask_b32_e32 v248, 0, v18, vcc

.LBB0_620:
	s_or_b64 exec, exec, s[84:85]
	v_mfma_f32_32x32x16_bf16 v[18:33], v[38:41], v[58:61], 0
	v_mfma_f32_32x32x16_bf16 v[18:33], v[46:49], v[54:57], v[18:33]
	v_mfma_f32_32x32x16_bf16 v[18:33], v[34:37], v[50:53], v[18:33]
	v_mfma_f32_32x32x16_bf16 v[18:33], v[42:45], v[62:65], v[18:33]
	s_waitcnt vmcnt(12)
	ds_read_b128 v[58:61], v74 offset:0
	ds_read_b128 v[54:57], v75 offset:0
	ds_read_b128 v[50:53], v76 offset:0
	ds_read_b128 v[62:65], v77 offset:0
	s_nop 8
	v_max_f32_e32 v18, 0, v18
	v_max_f32_e32 v19, 0, v19
	v_fma_f32 v18, v174, v18, 0
	v_max_f32_e32 v20, 0, v20
	v_fmac_f32_e32 v18, v173, v19
	v_max_f32_e32 v21, 0, v21
	v_fmac_f32_e32 v18, v172, v20
	v_max_f32_e32 v22, 0, v22
	v_fmac_f32_e32 v18, v171, v21
	v_max_f32_e32 v23, 0, v23
	v_fmac_f32_e32 v18, v170, v22
	v_max_f32_e32 v24, 0, v24
	v_fmac_f32_e32 v18, v169, v23
	v_max_f32_e32 v25, 0, v25
	v_fmac_f32_e32 v18, v168, v24
	v_max_f32_e32 v26, 0, v26
	v_fmac_f32_e32 v18, v167, v25
	v_max_f32_e32 v27, 0, v27
	v_fmac_f32_e32 v18, v166, v26
	v_max_f32_e32 v28, 0, v28
	v_fmac_f32_e32 v18, v165, v27
	v_max_f32_e32 v29, 0, v29
	v_fmac_f32_e32 v18, v164, v28
	v_max_f32_e32 v30, 0, v30
	v_fmac_f32_e32 v18, v163, v29
	v_fmac_f32_e32 v18, v162, v30
	v_max_f32_e32 v19, 0, v31
	v_fmac_f32_e32 v18, v161, v19
	v_max_f32_e32 v19, 0, v32
	v_fmac_f32_e32 v18, v160, v19
	v_max_f32_e32 v19, 0, v33
	v_fmac_f32_e32 v18, v89, v19
	v_not_b32_e32 v19, v18
	v_or_b32_e32 v20, 0x80000000, v18
	v_cmp_gt_i32_e32 vcc, 0, v18
	s_nop 1
	v_cndmask_b32_e32 v18, v20, v19, vcc
	v_cmp_le_u32_e32 vcc, v150, v87
	s_nop 1
	v_cndmask_b32_e32 v249, 0, v18, vcc

.LBB0_624:
	s_or_b64 exec, exec, s[84:85]
	v_mfma_f32_32x32x16_bf16 v[18:33], v[38:41], v[58:61], 0
	v_mfma_f32_32x32x16_bf16 v[18:33], v[46:49], v[54:57], v[18:33]
	v_mfma_f32_32x32x16_bf16 v[18:33], v[34:37], v[50:53], v[18:33]
	v_mfma_f32_32x32x16_bf16 v[18:33], v[42:45], v[62:65], v[18:33]
	s_waitcnt vmcnt(12)
	ds_read_b128 v[58:61], v74 offset:4096
	ds_read_b128 v[54:57], v75 offset:4096
	ds_read_b128 v[50:53], v76 offset:4096
	ds_read_b128 v[62:65], v77 offset:4096
	s_nop 8
	v_max_f32_e32 v18, 0, v18
	v_max_f32_e32 v19, 0, v19
	v_fma_f32 v18, v174, v18, 0
	v_max_f32_e32 v20, 0, v20
	v_fmac_f32_e32 v18, v173, v19
	v_max_f32_e32 v21, 0, v21
	v_fmac_f32_e32 v18, v172, v20
	v_max_f32_e32 v22, 0, v22
	v_fmac_f32_e32 v18, v171, v21
	v_max_f32_e32 v23, 0, v23
	v_fmac_f32_e32 v18, v170, v22
	v_max_f32_e32 v24, 0, v24
	v_fmac_f32_e32 v18, v169, v23
	v_max_f32_e32 v25, 0, v25
	v_fmac_f32_e32 v18, v168, v24
	v_max_f32_e32 v26, 0, v26
	v_fmac_f32_e32 v18, v167, v25
	v_max_f32_e32 v27, 0, v27
	v_fmac_f32_e32 v18, v166, v26
	v_max_f32_e32 v28, 0, v28
	v_fmac_f32_e32 v18, v165, v27
	v_max_f32_e32 v29, 0, v29
	v_fmac_f32_e32 v18, v164, v28
	v_max_f32_e32 v30, 0, v30
	v_fmac_f32_e32 v18, v163, v29
	v_fmac_f32_e32 v18, v162, v30
	v_max_f32_e32 v19, 0, v31
	v_fmac_f32_e32 v18, v161, v19
	v_max_f32_e32 v19, 0, v32
	v_fmac_f32_e32 v18, v160, v19
	v_max_f32_e32 v19, 0, v33
	v_fmac_f32_e32 v18, v89, v19
	v_not_b32_e32 v19, v18
	v_or_b32_e32 v20, 0x80000000, v18
	v_cmp_gt_i32_e32 vcc, 0, v18
	s_nop 1
	v_cndmask_b32_e32 v18, v20, v19, vcc
	v_cmp_le_u32_e32 vcc, v151, v87
	s_nop 1
	v_cndmask_b32_e32 v250, 0, v18, vcc

.LBB0_628:
	s_or_b64 exec, exec, s[84:85]
	v_mfma_f32_32x32x16_bf16 v[18:33], v[38:41], v[58:61], 0
	v_mfma_f32_32x32x16_bf16 v[18:33], v[46:49], v[54:57], v[18:33]
	v_mfma_f32_32x32x16_bf16 v[18:33], v[34:37], v[50:53], v[18:33]
	v_mfma_f32_32x32x16_bf16 v[18:33], v[42:45], v[62:65], v[18:33]
	s_waitcnt vmcnt(12)
	ds_read_b128 v[58:61], v74 offset:8192
	ds_read_b128 v[54:57], v75 offset:8192
	ds_read_b128 v[50:53], v76 offset:8192
	ds_read_b128 v[62:65], v77 offset:8192
	s_nop 8
	v_max_f32_e32 v18, 0, v18
	v_max_f32_e32 v19, 0, v19
	v_fma_f32 v18, v174, v18, 0
	v_max_f32_e32 v20, 0, v20
	v_fmac_f32_e32 v18, v173, v19
	v_max_f32_e32 v21, 0, v21
	v_fmac_f32_e32 v18, v172, v20
	v_max_f32_e32 v22, 0, v22
	v_fmac_f32_e32 v18, v171, v21
	v_max_f32_e32 v23, 0, v23
	v_fmac_f32_e32 v18, v170, v22
	v_max_f32_e32 v24, 0, v24
	v_fmac_f32_e32 v18, v169, v23
	v_max_f32_e32 v25, 0, v25
	v_fmac_f32_e32 v18, v168, v24
	v_max_f32_e32 v26, 0, v26
	v_fmac_f32_e32 v18, v167, v25
	v_max_f32_e32 v27, 0, v27
	v_fmac_f32_e32 v18, v166, v26
	v_max_f32_e32 v28, 0, v28
	v_fmac_f32_e32 v18, v165, v27
	v_max_f32_e32 v29, 0, v29
	v_fmac_f32_e32 v18, v164, v28
	v_max_f32_e32 v30, 0, v30
	v_fmac_f32_e32 v18, v163, v29
	v_fmac_f32_e32 v18, v162, v30
	v_max_f32_e32 v19, 0, v31
	v_fmac_f32_e32 v18, v161, v19
	v_max_f32_e32 v19, 0, v32
	v_fmac_f32_e32 v18, v160, v19
	v_max_f32_e32 v19, 0, v33
	v_fmac_f32_e32 v18, v89, v19
	v_not_b32_e32 v19, v18
	v_or_b32_e32 v20, 0x80000000, v18
	v_cmp_gt_i32_e32 vcc, 0, v18
	s_nop 1
	v_cndmask_b32_e32 v18, v20, v19, vcc
	v_cmp_le_u32_e32 vcc, v152, v87
	s_nop 1
	v_cndmask_b32_e32 v199, 0, v18, vcc

.LBB0_632:
	s_or_b64 exec, exec, s[84:85]
	v_mfma_f32_32x32x16_bf16 v[18:33], v[38:41], v[58:61], 0
	v_mfma_f32_32x32x16_bf16 v[18:33], v[46:49], v[54:57], v[18:33]
	v_mfma_f32_32x32x16_bf16 v[18:33], v[34:37], v[50:53], v[18:33]
	v_mfma_f32_32x32x16_bf16 v[18:33], v[42:45], v[62:65], v[18:33]
	s_waitcnt vmcnt(12)
	ds_read_b128 v[58:61], v74 offset:12288
	ds_read_b128 v[54:57], v75 offset:12288
	ds_read_b128 v[50:53], v76 offset:12288
	ds_read_b128 v[62:65], v77 offset:12288
	s_nop 8
	v_max_f32_e32 v18, 0, v18
	v_max_f32_e32 v19, 0, v19
	v_fma_f32 v18, v174, v18, 0
	v_max_f32_e32 v20, 0, v20
	v_fmac_f32_e32 v18, v173, v19
	v_max_f32_e32 v21, 0, v21
	v_fmac_f32_e32 v18, v172, v20
	v_max_f32_e32 v22, 0, v22
	v_fmac_f32_e32 v18, v171, v21
	v_max_f32_e32 v23, 0, v23
	v_fmac_f32_e32 v18, v170, v22
	v_max_f32_e32 v24, 0, v24
	v_fmac_f32_e32 v18, v169, v23
	v_max_f32_e32 v25, 0, v25
	v_fmac_f32_e32 v18, v168, v24
	v_max_f32_e32 v26, 0, v26
	v_fmac_f32_e32 v18, v167, v25
	v_max_f32_e32 v27, 0, v27
	v_fmac_f32_e32 v18, v166, v26
	v_max_f32_e32 v28, 0, v28
	v_fmac_f32_e32 v18, v165, v27
	v_max_f32_e32 v29, 0, v29
	v_fmac_f32_e32 v18, v164, v28
	v_max_f32_e32 v30, 0, v30
	v_fmac_f32_e32 v18, v163, v29
	v_fmac_f32_e32 v18, v162, v30
	v_max_f32_e32 v19, 0, v31
	v_fmac_f32_e32 v18, v161, v19
	v_max_f32_e32 v19, 0, v32
	v_fmac_f32_e32 v18, v160, v19
	v_max_f32_e32 v19, 0, v33
	v_fmac_f32_e32 v18, v89, v19
	v_not_b32_e32 v19, v18
	v_or_b32_e32 v20, 0x80000000, v18
	v_cmp_gt_i32_e32 vcc, 0, v18
	s_nop 1
	v_cndmask_b32_e32 v18, v20, v19, vcc
	v_cmp_le_u32_e32 vcc, v153, v87
	s_nop 1
	v_cndmask_b32_e32 v200, 0, v18, vcc

.LBB0_636:
	s_or_b64 exec, exec, s[84:85]
	v_mfma_f32_32x32x16_bf16 v[18:33], v[38:41], v[58:61], 0
	v_mfma_f32_32x32x16_bf16 v[18:33], v[46:49], v[54:57], v[18:33]
	v_mfma_f32_32x32x16_bf16 v[18:33], v[34:37], v[50:53], v[18:33]
	v_mfma_f32_32x32x16_bf16 v[18:33], v[42:45], v[62:65], v[18:33]
	s_waitcnt vmcnt(12)
	ds_read_b128 v[58:61], v74 offset:0
	ds_read_b128 v[54:57], v75 offset:0
	ds_read_b128 v[50:53], v76 offset:0
	ds_read_b128 v[62:65], v77 offset:0
	s_nop 8
	v_max_f32_e32 v18, 0, v18
	v_max_f32_e32 v19, 0, v19
	v_fma_f32 v18, v174, v18, 0
	v_max_f32_e32 v20, 0, v20
	v_fmac_f32_e32 v18, v173, v19
	v_max_f32_e32 v21, 0, v21
	v_fmac_f32_e32 v18, v172, v20
	v_max_f32_e32 v22, 0, v22
	v_fmac_f32_e32 v18, v171, v21
	v_max_f32_e32 v23, 0, v23
	v_fmac_f32_e32 v18, v170, v22
	v_max_f32_e32 v24, 0, v24
	v_fmac_f32_e32 v18, v169, v23
	v_max_f32_e32 v25, 0, v25
	v_fmac_f32_e32 v18, v168, v24
	v_max_f32_e32 v26, 0, v26
	v_fmac_f32_e32 v18, v167, v25
	v_max_f32_e32 v27, 0, v27
	v_fmac_f32_e32 v18, v166, v26
	v_max_f32_e32 v28, 0, v28
	v_fmac_f32_e32 v18, v165, v27
	v_max_f32_e32 v29, 0, v29
	v_fmac_f32_e32 v18, v164, v28
	v_max_f32_e32 v30, 0, v30
	v_fmac_f32_e32 v18, v163, v29
	v_fmac_f32_e32 v18, v162, v30
	v_max_f32_e32 v19, 0, v31
	v_fmac_f32_e32 v18, v161, v19
	v_max_f32_e32 v19, 0, v32
	v_fmac_f32_e32 v18, v160, v19
	v_max_f32_e32 v19, 0, v33
	v_fmac_f32_e32 v18, v89, v19
	v_not_b32_e32 v19, v18
	v_or_b32_e32 v20, 0x80000000, v18
	v_cmp_gt_i32_e32 vcc, 0, v18
	s_nop 1
	v_cndmask_b32_e32 v18, v20, v19, vcc
	v_cmp_le_u32_e32 vcc, v154, v87
	s_nop 1
	v_cndmask_b32_e32 v207, 0, v18, vcc

.LBB0_640:
	s_or_b64 exec, exec, s[84:85]
	v_mfma_f32_32x32x16_bf16 v[18:33], v[38:41], v[58:61], 0
	v_mfma_f32_32x32x16_bf16 v[18:33], v[46:49], v[54:57], v[18:33]
	v_mfma_f32_32x32x16_bf16 v[18:33], v[34:37], v[50:53], v[18:33]
	v_mfma_f32_32x32x16_bf16 v[18:33], v[42:45], v[62:65], v[18:33]
	s_waitcnt vmcnt(8)
	ds_read_b128 v[58:61], v74 offset:4096
	ds_read_b128 v[54:57], v75 offset:4096
	ds_read_b128 v[50:53], v76 offset:4096
	ds_read_b128 v[62:65], v77 offset:4096
	s_nop 8
	v_max_f32_e32 v18, 0, v18
	v_max_f32_e32 v19, 0, v19
	v_fma_f32 v18, v174, v18, 0
	v_max_f32_e32 v20, 0, v20
	v_fmac_f32_e32 v18, v173, v19
	v_max_f32_e32 v21, 0, v21
	v_fmac_f32_e32 v18, v172, v20
	v_max_f32_e32 v22, 0, v22
	v_fmac_f32_e32 v18, v171, v21
	v_max_f32_e32 v23, 0, v23
	v_fmac_f32_e32 v18, v170, v22
	v_max_f32_e32 v24, 0, v24
	v_fmac_f32_e32 v18, v169, v23
	v_max_f32_e32 v25, 0, v25
	v_fmac_f32_e32 v18, v168, v24
	v_max_f32_e32 v26, 0, v26
	v_fmac_f32_e32 v18, v167, v25
	v_max_f32_e32 v27, 0, v27
	v_fmac_f32_e32 v18, v166, v26
	v_max_f32_e32 v28, 0, v28
	v_fmac_f32_e32 v18, v165, v27
	v_max_f32_e32 v29, 0, v29
	v_fmac_f32_e32 v18, v164, v28
	v_max_f32_e32 v30, 0, v30
	v_fmac_f32_e32 v18, v163, v29
	v_fmac_f32_e32 v18, v162, v30
	v_max_f32_e32 v19, 0, v31
	v_fmac_f32_e32 v18, v161, v19
	v_max_f32_e32 v19, 0, v32
	v_fmac_f32_e32 v18, v160, v19
	v_max_f32_e32 v19, 0, v33
	v_fmac_f32_e32 v18, v89, v19
	v_not_b32_e32 v19, v18
	v_or_b32_e32 v20, 0x80000000, v18
	v_cmp_gt_i32_e32 vcc, 0, v18
	s_nop 1
	v_cndmask_b32_e32 v18, v20, v19, vcc
	v_cmp_le_u32_e32 vcc, v155, v87
	s_nop 1
	v_cndmask_b32_e32 v208, 0, v18, vcc

.LBB0_644:
	s_or_b64 exec, exec, s[84:85]
	v_mfma_f32_32x32x16_bf16 v[18:33], v[38:41], v[58:61], 0
	v_mfma_f32_32x32x16_bf16 v[18:33], v[46:49], v[54:57], v[18:33]
	v_mfma_f32_32x32x16_bf16 v[18:33], v[34:37], v[50:53], v[18:33]
	v_mfma_f32_32x32x16_bf16 v[18:33], v[42:45], v[62:65], v[18:33]
	s_waitcnt vmcnt(4)
	ds_read_b128 v[58:61], v74 offset:8192
	ds_read_b128 v[54:57], v75 offset:8192
	ds_read_b128 v[50:53], v76 offset:8192
	ds_read_b128 v[62:65], v77 offset:8192
	s_nop 8
	v_max_f32_e32 v18, 0, v18
	v_max_f32_e32 v19, 0, v19
	v_fma_f32 v18, v174, v18, 0
	v_max_f32_e32 v20, 0, v20
	v_fmac_f32_e32 v18, v173, v19
	v_max_f32_e32 v21, 0, v21
	v_fmac_f32_e32 v18, v172, v20
	v_max_f32_e32 v22, 0, v22
	v_fmac_f32_e32 v18, v171, v21
	v_max_f32_e32 v23, 0, v23
	v_fmac_f32_e32 v18, v170, v22
	v_max_f32_e32 v24, 0, v24
	v_fmac_f32_e32 v18, v169, v23
	v_max_f32_e32 v25, 0, v25
	v_fmac_f32_e32 v18, v168, v24
	v_max_f32_e32 v26, 0, v26
	v_fmac_f32_e32 v18, v167, v25
	v_max_f32_e32 v27, 0, v27
	v_fmac_f32_e32 v18, v166, v26
	v_max_f32_e32 v28, 0, v28
	v_fmac_f32_e32 v18, v165, v27
	v_max_f32_e32 v29, 0, v29
	v_fmac_f32_e32 v18, v164, v28
	v_max_f32_e32 v30, 0, v30
	v_fmac_f32_e32 v18, v163, v29
	v_fmac_f32_e32 v18, v162, v30
	v_max_f32_e32 v19, 0, v31
	v_fmac_f32_e32 v18, v161, v19
	v_max_f32_e32 v19, 0, v32
	v_fmac_f32_e32 v18, v160, v19
	v_max_f32_e32 v19, 0, v33
	v_fmac_f32_e32 v18, v89, v19
	v_not_b32_e32 v19, v18
	v_or_b32_e32 v20, 0x80000000, v18
	v_cmp_gt_i32_e32 vcc, 0, v18
	s_nop 1
	v_cndmask_b32_e32 v18, v20, v19, vcc
	v_cmp_le_u32_e32 vcc, v156, v87
	s_nop 1
	v_cndmask_b32_e32 v210, 0, v18, vcc

.LBB0_648:
	s_or_b64 exec, exec, s[84:85]
	v_mfma_f32_32x32x16_bf16 v[18:33], v[38:41], v[58:61], 0
	v_mfma_f32_32x32x16_bf16 v[18:33], v[46:49], v[54:57], v[18:33]
	v_mfma_f32_32x32x16_bf16 v[18:33], v[34:37], v[50:53], v[18:33]
	v_mfma_f32_32x32x16_bf16 v[18:33], v[42:45], v[62:65], v[18:33]
	s_waitcnt vmcnt(0)
	ds_read_b128 v[58:61], v74 offset:12288
	ds_read_b128 v[54:57], v75 offset:12288
	ds_read_b128 v[50:53], v76 offset:12288
	ds_read_b128 v[62:65], v77 offset:12288
	s_nop 8
	v_max_f32_e32 v18, 0, v18
	v_max_f32_e32 v19, 0, v19
	v_fma_f32 v18, v174, v18, 0
	v_max_f32_e32 v20, 0, v20
	v_fmac_f32_e32 v18, v173, v19
	v_max_f32_e32 v21, 0, v21
	v_fmac_f32_e32 v18, v172, v20
	v_max_f32_e32 v22, 0, v22
	v_fmac_f32_e32 v18, v171, v21
	v_max_f32_e32 v23, 0, v23
	v_fmac_f32_e32 v18, v170, v22
	v_max_f32_e32 v24, 0, v24
	v_fmac_f32_e32 v18, v169, v23
	v_max_f32_e32 v25, 0, v25
	v_fmac_f32_e32 v18, v168, v24
	v_max_f32_e32 v26, 0, v26
	v_fmac_f32_e32 v18, v167, v25
	v_max_f32_e32 v27, 0, v27
	v_fmac_f32_e32 v18, v166, v26
	v_max_f32_e32 v28, 0, v28
	v_fmac_f32_e32 v18, v165, v27
	v_max_f32_e32 v29, 0, v29
	v_fmac_f32_e32 v18, v164, v28
	v_max_f32_e32 v30, 0, v30
	v_fmac_f32_e32 v18, v163, v29
	v_fmac_f32_e32 v18, v162, v30
	v_max_f32_e32 v19, 0, v31
	v_fmac_f32_e32 v18, v161, v19
	v_max_f32_e32 v19, 0, v32
	v_fmac_f32_e32 v18, v160, v19
	v_max_f32_e32 v19, 0, v33
	v_fmac_f32_e32 v18, v89, v19
	v_not_b32_e32 v19, v18
	v_or_b32_e32 v20, 0x80000000, v18
	v_cmp_gt_i32_e32 vcc, 0, v18
	s_nop 1
	v_cndmask_b32_e32 v18, v20, v19, vcc
	v_cmp_le_u32_e32 vcc, v157, v87
	s_nop 1
	v_cndmask_b32_e32 v70, 0, v18, vcc
.LBB0_649:
	s_or_b64 exec, exec, s[82:83]
	v_cmp_eq_u32_e32 vcc, 63, v201
	v_mov_b32_e32 v66, 0
	v_mov_b32_e32 v18, 0
	s_and_saveexec_b64 s[82:83], vcc
	s_cbranch_execz .LBB0_651
	s_waitcnt lgkmcnt(0)
	v_mfma_f32_32x32x16_bf16 v[18:33], v[38:41], v[58:61], 0
	v_mfma_f32_32x32x16_bf16 v[18:33], v[46:49], v[54:57], v[18:33]
	v_mfma_f32_32x32x16_bf16 v[18:33], v[34:37], v[50:53], v[18:33]
	v_mfma_f32_32x32x16_bf16 v[18:33], v[42:45], v[62:65], v[18:33]
	s_nop 11
	v_max_f32_e32 v18, 0, v18
	v_max_f32_e32 v19, 0, v19
	v_fma_f32 v18, v174, v18, 0
	v_max_f32_e32 v20, 0, v20
	v_fmac_f32_e32 v18, v173, v19
	v_max_f32_e32 v21, 0, v21
	v_fmac_f32_e32 v18, v172, v20
	v_max_f32_e32 v22, 0, v22
	v_fmac_f32_e32 v18, v171, v21
	v_max_f32_e32 v23, 0, v23
	v_fmac_f32_e32 v18, v170, v22
	v_max_f32_e32 v24, 0, v24
	v_fmac_f32_e32 v18, v169, v23
	v_max_f32_e32 v25, 0, v25
	v_fmac_f32_e32 v18, v168, v24
	v_max_f32_e32 v26, 0, v26
	v_fmac_f32_e32 v18, v167, v25
	v_max_f32_e32 v27, 0, v27
	v_fmac_f32_e32 v18, v166, v26
	v_max_f32_e32 v28, 0, v28
	v_fmac_f32_e32 v18, v165, v27
	v_max_f32_e32 v29, 0, v29
	v_fmac_f32_e32 v18, v164, v28
	v_max_f32_e32 v30, 0, v30
	v_fmac_f32_e32 v18, v163, v29
	v_max_f32_e32 v31, 0, v31
	v_fmac_f32_e32 v18, v162, v30
	v_max_f32_e32 v32, 0, v32
	v_fmac_f32_e32 v18, v161, v31
	v_fmac_f32_e32 v18, v160, v32
	v_max_f32_e32 v19, 0, v33
	v_fmac_f32_e32 v18, v89, v19
	v_not_b32_e32 v19, v18
	v_or_b32_e32 v20, 0x80000000, v18
	v_cmp_gt_i32_e32 vcc, 0, v18
	s_nop 1
	v_cndmask_b32_e32 v18, v20, v19, vcc
	v_cmp_le_u32_e32 vcc, v158, v87
	s_nop 1
	v_cndmask_b32_e32 v18, 0, v18, vcc
.LBB0_651:
	s_or_b64 exec, exec, s[82:83]
	v_max_f32_e32 v2, 0, v2
	v_fma_f32 v2, v174, v2, 0
	v_max_f32_e32 v3, 0, v3
	v_fmac_f32_e32 v2, v173, v3
	v_max_f32_e32 v3, 0, v4
	v_fmac_f32_e32 v2, v172, v3
	v_max_f32_e32 v3, 0, v5
	v_fmac_f32_e32 v2, v171, v3
	v_max_f32_e32 v3, 0, v6
	v_fmac_f32_e32 v2, v170, v3
	v_max_f32_e32 v3, 0, v7
	v_fmac_f32_e32 v2, v169, v3
	v_max_f32_e32 v3, 0, v8
	v_fmac_f32_e32 v2, v168, v3
	v_max_f32_e32 v3, 0, v9
	v_fmac_f32_e32 v2, v167, v3
	v_max_f32_e32 v3, 0, v10
	v_fmac_f32_e32 v2, v166, v3
	v_max_f32_e32 v3, 0, v11
	v_fmac_f32_e32 v2, v165, v3
	v_max_f32_e32 v3, 0, v12
	v_fmac_f32_e32 v2, v164, v3
	v_max_f32_e32 v3, 0, v13
	v_fmac_f32_e32 v2, v163, v3
	v_max_f32_e32 v3, 0, v14
	v_fmac_f32_e32 v2, v162, v3
	v_max_f32_e32 v3, 0, v15
	v_fmac_f32_e32 v2, v161, v3
	v_max_f32_e32 v3, 0, v16
	v_fmac_f32_e32 v2, v160, v3
	v_max_f32_e32 v3, 0, v17
	v_fmac_f32_e32 v2, v89, v3
	v_not_b32_e32 v3, v2
	v_or_b32_e32 v4, 0x80000000, v2
	v_cmp_gt_i32_e32 vcc, 0, v2
	s_nop 1
	v_cndmask_b32_e32 v2, v4, v3, vcc
	v_cmp_le_u32_e32 vcc, v93, v87
	s_nop 1
	v_cndmask_b32_e32 v3, 0, v2, vcc
	v_mov_b32_e32 v2, 31
	v_readfirstlane_b32 s100, v177
	s_nop 1
	s_add_i32 s100, s100, 1
	s_lshr_b32 m0, s100, 5
	s_branch .LBB0_654
